# merge GEMM K-loop fully unrolled with two register staging sets (prefetch distance 2); upper half of the gated-sum accumulators parked in free LDS during each branch K-loop
# speedup vs baseline: 1.0059x; 1.0059x over previous
;   __device__ __forceinline__ half_t* u() const { return (half_t*)(ws() + OFF_u); }
;   __device__ __forceinline__ half_t* wpT() const { return (half_t*)(ws() + OFF_wpT); }
;   __device__ __forceinline__ half_t* ya() const { return (half_t*)(ws() + OFF_ya); }
;   __device__ __forceinline__ half_t* yb() const { return (half_t*)(ws() + OFF_yb); }
;   __device__ __forceinline__ half_t* yc() const { return (half_t*)(ws() + OFF_yc); }
; template <int NI, class LA, class LB, class EP>
; __device__ __forceinline__ void gemm_tile(int K, LA loadA, LB loadB, EP epi, char* smem) {
;     ...
;   f32x16 acc[2][NI];
; #pragma unroll
;   for (int i = 0; i < 2; ++i)
; #pragma unroll
;     for (int j = 0; j < NI; ++j)
; #pragma unroll
;       for (int r = 0; r < 16; ++r) acc[i][j][r] = 0.f;
;   const int lr = tid >> 3, lc = (tid & 7) * 8;
;   uint4 ra[4], rb[NB];
; #pragma unroll
;   for (int i = 0; i < 4; ++i) ra[i] = loadA(lr + 32 * i, lc);
; #pragma unroll
;   for (int i = 0; i < NB; ++i) rb[i] = loadB(lr + 32 * i, lc);
; __device__ __forceinline__ void phase_merge(const KP& p, char* smem, int* q, int xcc) {
;     ...
;     for (int br = 0; br < 3; ++br) {
;       const half_t* A = (br == 0 ? p.ya() : (br == 1 ? p.yb() : p.yc())) + (size_t)m0 * 512;
;       const half_t* B = p.wpT() + (size_t)br * DM * 512 + (size_t)n0 * 512;
;       const half_t* G = p.u() + (size_t)m0 * NU + C_GM + br * 1024 + n0;
;       gemm_tile<2>(
.LBB0_1742:
	v_lshlrev_b32_e32 v90, 4, v224
	v_add_u32_e32 v90, 0x9000, v90
	ds_write_b128 v90, v[130:133]
	ds_write_b128 v90, v[134:137] offset:4096
	ds_write_b128 v90, v[138:141] offset:8192
	ds_write_b128 v90, v[142:145] offset:12288
	ds_write_b128 v90, v[146:149] offset:16384
	ds_write_b128 v90, v[150:153] offset:20480
	ds_write_b128 v90, v[154:157] offset:24576
	ds_write_b128 v90, v[158:161] offset:28672
	s_cmp_eq_u32 s56, 1
	s_mov_b32 s2, 0x174a0200
	s_cselect_b32 s2, s2, 0x184a0200
	s_cmp_lg_u32 s56, 0
	v_mov_b32_e32 v169, v224
	s_cselect_b32 s57, s2, 0x164a0200
	s_add_u32 s2, s15, s57
	v_lshlrev_b32_e32 v0, 3, v169
	v_ashrrev_i32_e32 v2, 3, v169
	v_and_b32_e32 v16, 56, v0
	s_addc_u32 s3, s49, 0
	v_lshlrev_b32_e32 v0, 1, v16
	v_ashrrev_i32_e32 v3, 31, v2
	v_lshl_add_u64 v[4:5], s[2:3], 0, v[0:1]
	v_lshlrev_b64 v[6:7], 10, v[2:3]
	s_mov_b64 s[2:3], 0x8000
	s_lshl_b32 s40, s56, 20
	v_lshl_add_u64 v[8:9], v[4:5], 0, v[6:7]
	v_lshl_add_u64 v[10:11], v[6:7], 0, s[2:3]
	s_mov_b64 s[2:3], 0x18000
	s_add_u32 s40, s50, s40
	v_lshl_add_u64 v[12:13], v[4:5], 0, v[10:11]
	global_load_dwordx4 v[192:195], v[8:9], off
	global_load_dwordx4 v[196:199], v[12:13], off
	v_lshl_add_u64 v[8:9], v[6:7], 0, s[20:21]
	v_lshl_add_u64 v[14:15], v[6:7], 0, s[2:3]
	s_addc_u32 s41, s51, 0
	v_lshl_add_u64 v[12:13], v[4:5], 0, v[8:9]
	v_lshl_add_u64 v[4:5], v[4:5], 0, v[14:15]
	global_load_dwordx4 v[200:203], v[12:13], off
	global_load_dwordx4 v[204:207], v[4:5], off
	v_lshl_add_u64 v[4:5], s[40:41], 0, v[0:1]
	v_lshl_add_u64 v[12:13], v[4:5], 0, v[6:7]
	v_lshl_add_u64 v[8:9], v[4:5], 0, v[8:9]
	v_lshl_add_u64 v[10:11], v[4:5], 0, v[10:11]
	global_load_dwordx4 v[208:211], v[12:13], off
	global_load_dwordx4 v[212:215], v[10:11], off
	v_lshl_add_u64 v[4:5], v[4:5], 0, v[14:15]
	global_load_dwordx4 v[216:219], v[8:9], off
	global_load_dwordx4 v[220:223], v[4:5], off
	v_ashrrev_i32_e32 v0, 1, v169
	v_and_b32_e32 v170, 0xffffffc0, v0
	v_lshrrev_b32_e32 v4, 1, v169
	v_and_or_b32 v3, v169, 31, v170
	v_and_b32_e32 v0, 0x5f, v169
	v_and_b32_e32 v4, 16, v4
	v_mul_lo_u32 v2, v2, s37
	v_mad_u64_u32 v[162:163], s[2:3], v3, s36, v[4:5]
	v_add_lshl_u32 v172, v2, v16, 1
	v_mul_u32_u24_e32 v2, 0x48, v0
	v_lshl_add_u32 v163, v2, 1, v4
	v_and_b32_e32 v2, 7, v169
	s_add_u32 s2, s54, s57
	v_lshl_or_b32 v6, v2, 4, v6
	s_addc_u32 s3, s55, 0
	v_add_u32_e32 v171, 0x1200, v163
	v_lshl_add_u64 v[164:165], s[38:39], 0, v[6:7]
	v_lshl_add_u64 v[166:167], s[2:3], 0, v[6:7]
	s_mov_b64 s[2:3], 0x80
	v_lshl_add_u64 v[228:229], v[166:167], 0, s[2:3]
	s_nop 0
	v_add_co_u32_e32 v230, vcc, s73, v228
	s_nop 1
	v_addc_co_u32_e32 v231, vcc, 0, v229, vcc
	v_add_co_u32_e32 v232, vcc, s72, v228
	s_nop 1
	v_addc_co_u32_e32 v233, vcc, 0, v229, vcc
	v_add_co_u32_e32 v234, vcc, s77, v228
	s_nop 1
	v_addc_co_u32_e32 v235, vcc, 0, v229, vcc
	s_mov_b64 s[2:3], 0x15680080
	v_lshl_add_u64 v[238:239], v[164:165], 0, s[2:3]
	s_mov_b64 s[2:3], 0x15688080
	v_lshl_add_u64 v[240:241], v[164:165], 0, s[2:3]
	s_mov_b64 s[2:3], 0x15690080
	v_lshl_add_u64 v[242:243], v[164:165], 0, s[2:3]
	s_mov_b64 s[2:3], 0x15698080
	v_lshl_add_u64 v[244:245], v[164:165], 0, s[2:3]
	global_load_dwordx4 v[130:133], v[228:229], off
	global_load_dwordx4 v[134:137], v[230:231], off
	global_load_dwordx4 v[138:141], v[232:233], off
	global_load_dwordx4 v[142:145], v[234:235], off
	global_load_dwordx4 v[146:149], v[238:239], off
	global_load_dwordx4 v[150:153], v[240:241], off
	global_load_dwordx4 v[154:157], v[242:243], off
	global_load_dwordx4 v[158:161], v[244:245], off
	s_mov_b64 s[2:3], 0x80
	s_mov_b64 s[40:41], 0
	v_mov_b32_e32 v2, 0
	v_mov_b32_e32 v3, v168
	v_mov_b32_e32 v4, v168
	v_mov_b32_e32 v5, v168
	v_mov_b32_e32 v6, v168
	v_mov_b32_e32 v7, v168
	v_mov_b32_e32 v8, v168
	v_mov_b32_e32 v9, v168
	v_mov_b32_e32 v10, v168
	v_mov_b32_e32 v11, v168
	v_mov_b32_e32 v12, v168
	v_mov_b32_e32 v13, v168
	v_mov_b32_e32 v14, v168
	v_mov_b32_e32 v15, v168
	v_mov_b32_e32 v16, v168
	v_mov_b32_e32 v17, v168
	v_mov_b32_e32 v18, 0
	v_mov_b32_e32 v19, v168
	v_mov_b32_e32 v20, v168
	v_mov_b32_e32 v21, v168
	v_mov_b32_e32 v22, v168
	v_mov_b32_e32 v23, v168
	v_mov_b32_e32 v24, v168
	v_mov_b32_e32 v25, v168
	v_mov_b32_e32 v26, v168
	v_mov_b32_e32 v27, v168
	v_mov_b32_e32 v28, v168
	v_mov_b32_e32 v29, v168
	v_mov_b32_e32 v30, v168
	v_mov_b32_e32 v31, v168
	v_mov_b32_e32 v32, v168
	v_mov_b32_e32 v33, v168
	v_mov_b32_e32 v34, 0
	v_mov_b32_e32 v35, v168
	v_mov_b32_e32 v36, v168
	v_mov_b32_e32 v37, v168
	v_mov_b32_e32 v38, v168
	v_mov_b32_e32 v39, v168
	v_mov_b32_e32 v40, v168
	v_mov_b32_e32 v41, v168
	v_mov_b32_e32 v42, v168
	v_mov_b32_e32 v43, v168
	v_mov_b32_e32 v44, v168
	v_mov_b32_e32 v45, v168
	v_mov_b32_e32 v46, v168
	v_mov_b32_e32 v47, v168
	v_mov_b32_e32 v48, v168
	v_mov_b32_e32 v49, v168
	v_mov_b32_e32 v50, 0
	v_mov_b32_e32 v51, v168
	v_mov_b32_e32 v52, v168
	v_mov_b32_e32 v53, v168
	v_mov_b32_e32 v54, v168
	v_mov_b32_e32 v55, v168
	v_mov_b32_e32 v56, v168
	v_mov_b32_e32 v57, v168
	v_mov_b32_e32 v58, v168
	v_mov_b32_e32 v59, v168
	v_mov_b32_e32 v60, v168
	v_mov_b32_e32 v61, v168
	v_mov_b32_e32 v62, v168
	v_mov_b32_e32 v63, v168
	v_mov_b32_e32 v64, v168
	v_mov_b32_e32 v65, v168
; template <int NI, class LA, class LB, class EP>
; __device__ __forceinline__ void gemm_tile(int K, LA loadA, LB loadB, EP epi, char* smem) {
;     ...
;   for (int kt = 0; kt < nk; ++kt) {
;     __syncthreads();
; #pragma unroll
;     for (int i = 0; i < 4; ++i) *(uint4*)&sA[(lr + 32 * i) * 72 + lc] = ra[i];
; #pragma unroll
;     for (int i = 0; i < NB; ++i) *(uint4*)&sB[(lr + 32 * i) * 72 + lc] = rb[i];
;     __syncthreads();
;     if (kt + 1 < nk) {
;       const int kk = (kt + 1) * 64 + lc;
; #pragma unroll
;       for (int i = 0; i < 4; ++i) ra[i] = loadA(lr + 32 * i, kk);
; #pragma unroll
;       for (int i = 0; i < NB; ++i) rb[i] = loadB(lr + 32 * i, kk);
;     }
; #pragma unroll
;     for (int s = 0; s < 4; ++s) {
;       h8 af[2], bf[NI];
; #pragma unroll
;       for (int mi = 0; mi < 2; ++mi)
;         af[mi] = *(const h8*)&sA[(wm * 64 + mi * 32 + (lane & 31)) * 72 + s * 16 + (lane >> 5) * 8];
; #pragma unroll
;       for (int ni = 0; ni < NI; ++ni)
;         bf[ni] = *(const h8*)&sB[(wn * (NI * 32) + ni * 32 + (lane & 31)) * 72 + s * 16 + (lane >> 5) * 8];
; #pragma unroll
;       for (int mi = 0; mi < 2; ++mi)
; #pragma unroll
;         for (int ni = 0; ni < NI; ++ni)
;           acc[mi][ni] = __builtin_amdgcn_mfma_f32_32x32x16_f16(af[mi], bf[ni], acc[mi][ni], 0, 0, 0);
;     }
.LBB0_1743:
	s_waitcnt vmcnt(63) expcnt(7) lgkmcnt(15)
	s_barrier
	s_waitcnt vmcnt(15)
	ds_write_b128 v172, v[192:195]
	s_waitcnt vmcnt(14)
	ds_write_b128 v172, v[196:199] offset:4608
	s_waitcnt vmcnt(13)
	ds_write_b128 v172, v[200:203] offset:9216
	s_waitcnt vmcnt(12)
	ds_write_b128 v172, v[204:207] offset:13824
	s_waitcnt vmcnt(11)
	ds_write_b128 v172, v[208:211] offset:18432
	s_waitcnt vmcnt(10)
	ds_write_b128 v172, v[212:215] offset:23040
	s_waitcnt vmcnt(9)
	ds_write_b128 v172, v[216:219] offset:27648
	s_waitcnt vmcnt(8)
	ds_write_b128 v172, v[220:223] offset:32256
	global_load_dwordx4 v[192:195], v[228:229], off offset:128
	global_load_dwordx4 v[196:199], v[230:231], off offset:128
	global_load_dwordx4 v[200:203], v[232:233], off offset:128
	global_load_dwordx4 v[204:207], v[234:235], off offset:128
	global_load_dwordx4 v[208:211], v[238:239], off offset:128
	global_load_dwordx4 v[212:215], v[240:241], off offset:128
	global_load_dwordx4 v[216:219], v[242:243], off offset:128
	global_load_dwordx4 v[220:223], v[244:245], off offset:128
	s_waitcnt lgkmcnt(0)
	s_barrier
	ds_read_b128 v[66:69], v162
	ds_read_b128 v[70:73], v163 offset:18432
	ds_read_b128 v[74:77], v162 offset:32
	ds_read_b128 v[78:81], v163 offset:18464
	ds_read_b128 v[82:85], v171 offset:18432
	ds_read_b128 v[174:177], v163 offset:23136
	s_waitcnt lgkmcnt(4)
	v_mfma_f32_32x32x16_f16 v[50:65], v[66:69], v[70:73], v[50:65]
	s_waitcnt lgkmcnt(1)
	v_mfma_f32_32x32x16_f16 v[34:49], v[66:69], v[82:85], v[34:49]
	ds_read_b128 v[66:69], v162 offset:4608
	ds_read_b128 v[86:89], v162 offset:4640
	s_waitcnt lgkmcnt(1)
	v_mfma_f32_32x32x16_f16 v[18:33], v[66:69], v[70:73], v[18:33]
	v_mfma_f32_32x32x16_f16 v[2:17], v[66:69], v[82:85], v[2:17]
	ds_read_b128 v[66:69], v163 offset:23072
	ds_read_b128 v[70:73], v163 offset:23104
	v_mfma_f32_32x32x16_f16 v[50:65], v[74:77], v[78:81], v[50:65]
	s_waitcnt lgkmcnt(1)
	v_mfma_f32_32x32x16_f16 v[34:49], v[74:77], v[66:69], v[34:49]
	v_mfma_f32_32x32x16_f16 v[18:33], v[86:89], v[78:81], v[18:33]
	v_mfma_f32_32x32x16_f16 v[2:17], v[86:89], v[66:69], v[2:17]
	ds_read_b128 v[66:69], v162 offset:64
	ds_read_b128 v[74:77], v163 offset:18496
	ds_read_b128 v[78:81], v162 offset:96
	ds_read_b128 v[82:85], v163 offset:18528
	ds_read_b128 v[86:89], v162 offset:4672
	ds_read_b128 v[178:181], v162 offset:4704
	s_waitcnt lgkmcnt(4)
	v_mfma_f32_32x32x16_f16 v[50:65], v[66:69], v[74:77], v[50:65]
	v_mfma_f32_32x32x16_f16 v[34:49], v[66:69], v[70:73], v[34:49]
	s_waitcnt lgkmcnt(1)
	v_mfma_f32_32x32x16_f16 v[18:33], v[86:89], v[74:77], v[18:33]
	v_mfma_f32_32x32x16_f16 v[2:17], v[86:89], v[70:73], v[2:17]
	v_mfma_f32_32x32x16_f16 v[50:65], v[78:81], v[82:85], v[50:65]
	v_mfma_f32_32x32x16_f16 v[34:49], v[78:81], v[174:177], v[34:49]
	s_waitcnt lgkmcnt(0)
	v_mfma_f32_32x32x16_f16 v[18:33], v[178:181], v[82:85], v[18:33]
	v_mfma_f32_32x32x16_f16 v[2:17], v[178:181], v[174:177], v[2:17]
	s_barrier
	s_waitcnt vmcnt(15)
	ds_write_b128 v172, v[130:133]
	s_waitcnt vmcnt(14)
	ds_write_b128 v172, v[134:137] offset:4608
	s_waitcnt vmcnt(13)
	ds_write_b128 v172, v[138:141] offset:9216
	s_waitcnt vmcnt(12)
	ds_write_b128 v172, v[142:145] offset:13824
	s_waitcnt vmcnt(11)
	ds_write_b128 v172, v[146:149] offset:18432
	s_waitcnt vmcnt(10)
	ds_write_b128 v172, v[150:153] offset:23040
	s_waitcnt vmcnt(9)
	ds_write_b128 v172, v[154:157] offset:27648
	s_waitcnt vmcnt(8)
	ds_write_b128 v172, v[158:161] offset:32256
	global_load_dwordx4 v[130:133], v[228:229], off offset:256
	global_load_dwordx4 v[134:137], v[230:231], off offset:256
	global_load_dwordx4 v[138:141], v[232:233], off offset:256
	global_load_dwordx4 v[142:145], v[234:235], off offset:256
	global_load_dwordx4 v[146:149], v[238:239], off offset:256
	global_load_dwordx4 v[150:153], v[240:241], off offset:256
	global_load_dwordx4 v[154:157], v[242:243], off offset:256
	global_load_dwordx4 v[158:161], v[244:245], off offset:256
	s_waitcnt lgkmcnt(0)
	s_barrier
	ds_read_b128 v[66:69], v162
	ds_read_b128 v[70:73], v163 offset:18432
	ds_read_b128 v[74:77], v162 offset:32
	ds_read_b128 v[78:81], v163 offset:18464
	ds_read_b128 v[82:85], v171 offset:18432
	ds_read_b128 v[174:177], v163 offset:23136
	s_waitcnt lgkmcnt(4)
	v_mfma_f32_32x32x16_f16 v[50:65], v[66:69], v[70:73], v[50:65]
	s_waitcnt lgkmcnt(1)
	v_mfma_f32_32x32x16_f16 v[34:49], v[66:69], v[82:85], v[34:49]
	ds_read_b128 v[66:69], v162 offset:4608
	ds_read_b128 v[86:89], v162 offset:4640
	s_waitcnt lgkmcnt(1)
	v_mfma_f32_32x32x16_f16 v[18:33], v[66:69], v[70:73], v[18:33]
	v_mfma_f32_32x32x16_f16 v[2:17], v[66:69], v[82:85], v[2:17]
	ds_read_b128 v[66:69], v163 offset:23072
	ds_read_b128 v[70:73], v163 offset:23104
	v_mfma_f32_32x32x16_f16 v[50:65], v[74:77], v[78:81], v[50:65]
	s_waitcnt lgkmcnt(1)
	v_mfma_f32_32x32x16_f16 v[34:49], v[74:77], v[66:69], v[34:49]
	v_mfma_f32_32x32x16_f16 v[18:33], v[86:89], v[78:81], v[18:33]
	v_mfma_f32_32x32x16_f16 v[2:17], v[86:89], v[66:69], v[2:17]
	ds_read_b128 v[66:69], v162 offset:64
	ds_read_b128 v[74:77], v163 offset:18496
	ds_read_b128 v[78:81], v162 offset:96
	ds_read_b128 v[82:85], v163 offset:18528
	ds_read_b128 v[86:89], v162 offset:4672
	ds_read_b128 v[178:181], v162 offset:4704
	s_waitcnt lgkmcnt(4)
	v_mfma_f32_32x32x16_f16 v[50:65], v[66:69], v[74:77], v[50:65]
	v_mfma_f32_32x32x16_f16 v[34:49], v[66:69], v[70:73], v[34:49]
	s_waitcnt lgkmcnt(1)
	v_mfma_f32_32x32x16_f16 v[18:33], v[86:89], v[74:77], v[18:33]
	v_mfma_f32_32x32x16_f16 v[2:17], v[86:89], v[70:73], v[2:17]
	v_mfma_f32_32x32x16_f16 v[50:65], v[78:81], v[82:85], v[50:65]
	v_mfma_f32_32x32x16_f16 v[34:49], v[78:81], v[174:177], v[34:49]
	s_waitcnt lgkmcnt(0)
	v_mfma_f32_32x32x16_f16 v[18:33], v[178:181], v[82:85], v[18:33]
	v_mfma_f32_32x32x16_f16 v[2:17], v[178:181], v[174:177], v[2:17]
	s_barrier
; template <int NI, class LA, class LB, class EP>
; __device__ __forceinline__ void gemm_tile(int K, LA loadA, LB loadB, EP epi, char* smem) {
;     ...
;   for (int kt = 0; kt < nk; ++kt) {
;     __syncthreads();
; #pragma unroll
;     for (int i = 0; i < 4; ++i) *(uint4*)&sA[(lr + 32 * i) * 72 + lc] = ra[i];
; #pragma unroll
;     for (int i = 0; i < NB; ++i) *(uint4*)&sB[(lr + 32 * i) * 72 + lc] = rb[i];
;     __syncthreads();
;     if (kt + 1 < nk) {
;       const int kk = (kt + 1) * 64 + lc;
; #pragma unroll
;       for (int i = 0; i < 4; ++i) ra[i] = loadA(lr + 32 * i, kk);
; #pragma unroll
;       for (int i = 0; i < NB; ++i) rb[i] = loadB(lr + 32 * i, kk);
;     }
; #pragma unroll
;     for (int s = 0; s < 4; ++s) {
;       h8 af[2], bf[NI];
; #pragma unroll
;       for (int mi = 0; mi < 2; ++mi)
;         af[mi] = *(const h8*)&sA[(wm * 64 + mi * 32 + (lane & 31)) * 72 + s * 16 + (lane >> 5) * 8];
; #pragma unroll
;       for (int ni = 0; ni < NI; ++ni)
;         bf[ni] = *(const h8*)&sB[(wn * (NI * 32) + ni * 32 + (lane & 31)) * 72 + s * 16 + (lane >> 5) * 8];
; #pragma unroll
;       for (int mi = 0; mi < 2; ++mi)
; #pragma unroll
;         for (int ni = 0; ni < NI; ++ni)
;           acc[mi][ni] = __builtin_amdgcn_mfma_f32_32x32x16_f16(af[mi], bf[ni], acc[mi][ni], 0, 0, 0);
;     }
	s_waitcnt vmcnt(15)
	ds_write_b128 v172, v[192:195]
	s_waitcnt vmcnt(14)
	ds_write_b128 v172, v[196:199] offset:4608
	s_waitcnt vmcnt(13)
	ds_write_b128 v172, v[200:203] offset:9216
	s_waitcnt vmcnt(12)
	ds_write_b128 v172, v[204:207] offset:13824
	s_waitcnt vmcnt(11)
	ds_write_b128 v172, v[208:211] offset:18432
	s_waitcnt vmcnt(10)
	ds_write_b128 v172, v[212:215] offset:23040
	s_waitcnt vmcnt(9)
	ds_write_b128 v172, v[216:219] offset:27648
	s_waitcnt vmcnt(8)
	ds_write_b128 v172, v[220:223] offset:32256
	global_load_dwordx4 v[192:195], v[228:229], off offset:384
	global_load_dwordx4 v[196:199], v[230:231], off offset:384
	global_load_dwordx4 v[200:203], v[232:233], off offset:384
	global_load_dwordx4 v[204:207], v[234:235], off offset:384
	global_load_dwordx4 v[208:211], v[238:239], off offset:384
	global_load_dwordx4 v[212:215], v[240:241], off offset:384
	global_load_dwordx4 v[216:219], v[242:243], off offset:384
	global_load_dwordx4 v[220:223], v[244:245], off offset:384
	s_waitcnt lgkmcnt(0)
	s_barrier
	ds_read_b128 v[66:69], v162
	ds_read_b128 v[70:73], v163 offset:18432
	ds_read_b128 v[74:77], v162 offset:32
	ds_read_b128 v[78:81], v163 offset:18464
	ds_read_b128 v[82:85], v171 offset:18432
	ds_read_b128 v[174:177], v163 offset:23136
	s_waitcnt lgkmcnt(4)
	v_mfma_f32_32x32x16_f16 v[50:65], v[66:69], v[70:73], v[50:65]
	s_waitcnt lgkmcnt(1)
	v_mfma_f32_32x32x16_f16 v[34:49], v[66:69], v[82:85], v[34:49]
	ds_read_b128 v[66:69], v162 offset:4608
	ds_read_b128 v[86:89], v162 offset:4640
	s_waitcnt lgkmcnt(1)
	v_mfma_f32_32x32x16_f16 v[18:33], v[66:69], v[70:73], v[18:33]
	v_mfma_f32_32x32x16_f16 v[2:17], v[66:69], v[82:85], v[2:17]
	ds_read_b128 v[66:69], v163 offset:23072
	ds_read_b128 v[70:73], v163 offset:23104
	v_mfma_f32_32x32x16_f16 v[50:65], v[74:77], v[78:81], v[50:65]
	s_waitcnt lgkmcnt(1)
	v_mfma_f32_32x32x16_f16 v[34:49], v[74:77], v[66:69], v[34:49]
	v_mfma_f32_32x32x16_f16 v[18:33], v[86:89], v[78:81], v[18:33]
	v_mfma_f32_32x32x16_f16 v[2:17], v[86:89], v[66:69], v[2:17]
	ds_read_b128 v[66:69], v162 offset:64
	ds_read_b128 v[74:77], v163 offset:18496
	ds_read_b128 v[78:81], v162 offset:96
	ds_read_b128 v[82:85], v163 offset:18528
	ds_read_b128 v[86:89], v162 offset:4672
	ds_read_b128 v[178:181], v162 offset:4704
	s_waitcnt lgkmcnt(4)
	v_mfma_f32_32x32x16_f16 v[50:65], v[66:69], v[74:77], v[50:65]
	v_mfma_f32_32x32x16_f16 v[34:49], v[66:69], v[70:73], v[34:49]
	s_waitcnt lgkmcnt(1)
	v_mfma_f32_32x32x16_f16 v[18:33], v[86:89], v[74:77], v[18:33]
	v_mfma_f32_32x32x16_f16 v[2:17], v[86:89], v[70:73], v[2:17]
	v_mfma_f32_32x32x16_f16 v[50:65], v[78:81], v[82:85], v[50:65]
	v_mfma_f32_32x32x16_f16 v[34:49], v[78:81], v[174:177], v[34:49]
	s_waitcnt lgkmcnt(0)
	v_mfma_f32_32x32x16_f16 v[18:33], v[178:181], v[82:85], v[18:33]
	v_mfma_f32_32x32x16_f16 v[2:17], v[178:181], v[174:177], v[2:17]
	s_barrier
	s_waitcnt vmcnt(15)
	ds_write_b128 v172, v[130:133]
	s_waitcnt vmcnt(14)
	ds_write_b128 v172, v[134:137] offset:4608
	s_waitcnt vmcnt(13)
	ds_write_b128 v172, v[138:141] offset:9216
	s_waitcnt vmcnt(12)
	ds_write_b128 v172, v[142:145] offset:13824
	s_waitcnt vmcnt(11)
	ds_write_b128 v172, v[146:149] offset:18432
	s_waitcnt vmcnt(10)
	ds_write_b128 v172, v[150:153] offset:23040
	s_waitcnt vmcnt(9)
	ds_write_b128 v172, v[154:157] offset:27648
	s_waitcnt vmcnt(8)
	ds_write_b128 v172, v[158:161] offset:32256
	global_load_dwordx4 v[130:133], v[228:229], off offset:512
	global_load_dwordx4 v[134:137], v[230:231], off offset:512
	global_load_dwordx4 v[138:141], v[232:233], off offset:512
	global_load_dwordx4 v[142:145], v[234:235], off offset:512
	global_load_dwordx4 v[146:149], v[238:239], off offset:512
	global_load_dwordx4 v[150:153], v[240:241], off offset:512
	global_load_dwordx4 v[154:157], v[242:243], off offset:512
	global_load_dwordx4 v[158:161], v[244:245], off offset:512
	s_waitcnt lgkmcnt(0)
	s_barrier
	ds_read_b128 v[66:69], v162
	ds_read_b128 v[70:73], v163 offset:18432
	ds_read_b128 v[74:77], v162 offset:32
	ds_read_b128 v[78:81], v163 offset:18464
	ds_read_b128 v[82:85], v171 offset:18432
	ds_read_b128 v[174:177], v163 offset:23136
	s_waitcnt lgkmcnt(4)
	v_mfma_f32_32x32x16_f16 v[50:65], v[66:69], v[70:73], v[50:65]
	s_waitcnt lgkmcnt(1)
	v_mfma_f32_32x32x16_f16 v[34:49], v[66:69], v[82:85], v[34:49]
	ds_read_b128 v[66:69], v162 offset:4608
	ds_read_b128 v[86:89], v162 offset:4640
	s_waitcnt lgkmcnt(1)
	v_mfma_f32_32x32x16_f16 v[18:33], v[66:69], v[70:73], v[18:33]
	v_mfma_f32_32x32x16_f16 v[2:17], v[66:69], v[82:85], v[2:17]
	ds_read_b128 v[66:69], v163 offset:23072
	ds_read_b128 v[70:73], v163 offset:23104
	v_mfma_f32_32x32x16_f16 v[50:65], v[74:77], v[78:81], v[50:65]
	s_waitcnt lgkmcnt(1)
	v_mfma_f32_32x32x16_f16 v[34:49], v[74:77], v[66:69], v[34:49]
	v_mfma_f32_32x32x16_f16 v[18:33], v[86:89], v[78:81], v[18:33]
	v_mfma_f32_32x32x16_f16 v[2:17], v[86:89], v[66:69], v[2:17]
	ds_read_b128 v[66:69], v162 offset:64
	ds_read_b128 v[74:77], v163 offset:18496
	ds_read_b128 v[78:81], v162 offset:96
	ds_read_b128 v[82:85], v163 offset:18528
	ds_read_b128 v[86:89], v162 offset:4672
	ds_read_b128 v[178:181], v162 offset:4704
	s_waitcnt lgkmcnt(4)
	v_mfma_f32_32x32x16_f16 v[50:65], v[66:69], v[74:77], v[50:65]
	v_mfma_f32_32x32x16_f16 v[34:49], v[66:69], v[70:73], v[34:49]
	s_waitcnt lgkmcnt(1)
	v_mfma_f32_32x32x16_f16 v[18:33], v[86:89], v[74:77], v[18:33]
	v_mfma_f32_32x32x16_f16 v[2:17], v[86:89], v[70:73], v[2:17]
	v_mfma_f32_32x32x16_f16 v[50:65], v[78:81], v[82:85], v[50:65]
	v_mfma_f32_32x32x16_f16 v[34:49], v[78:81], v[174:177], v[34:49]
	s_waitcnt lgkmcnt(0)
	v_mfma_f32_32x32x16_f16 v[18:33], v[178:181], v[82:85], v[18:33]
	v_mfma_f32_32x32x16_f16 v[2:17], v[178:181], v[174:177], v[2:17]
	s_barrier
; template <int NI, class LA, class LB, class EP>
; __device__ __forceinline__ void gemm_tile(int K, LA loadA, LB loadB, EP epi, char* smem) {
;     ...
;   for (int kt = 0; kt < nk; ++kt) {
;     __syncthreads();
; #pragma unroll
;     for (int i = 0; i < 4; ++i) *(uint4*)&sA[(lr + 32 * i) * 72 + lc] = ra[i];
; #pragma unroll
;     for (int i = 0; i < NB; ++i) *(uint4*)&sB[(lr + 32 * i) * 72 + lc] = rb[i];
;     __syncthreads();
;     if (kt + 1 < nk) {
;       const int kk = (kt + 1) * 64 + lc;
; #pragma unroll
;       for (int i = 0; i < 4; ++i) ra[i] = loadA(lr + 32 * i, kk);
; #pragma unroll
;       for (int i = 0; i < NB; ++i) rb[i] = loadB(lr + 32 * i, kk);
;     }
; #pragma unroll
;     for (int s = 0; s < 4; ++s) {
;       h8 af[2], bf[NI];
; #pragma unroll
;       for (int mi = 0; mi < 2; ++mi)
;         af[mi] = *(const h8*)&sA[(wm * 64 + mi * 32 + (lane & 31)) * 72 + s * 16 + (lane >> 5) * 8];
; #pragma unroll
;       for (int ni = 0; ni < NI; ++ni)
;         bf[ni] = *(const h8*)&sB[(wn * (NI * 32) + ni * 32 + (lane & 31)) * 72 + s * 16 + (lane >> 5) * 8];
; #pragma unroll
;       for (int mi = 0; mi < 2; ++mi)
; #pragma unroll
;         for (int ni = 0; ni < NI; ++ni)
;           acc[mi][ni] = __builtin_amdgcn_mfma_f32_32x32x16_f16(af[mi], bf[ni], acc[mi][ni], 0, 0, 0);
;     }
	s_waitcnt vmcnt(15)
	ds_write_b128 v172, v[192:195]
	s_waitcnt vmcnt(14)
	ds_write_b128 v172, v[196:199] offset:4608
	s_waitcnt vmcnt(13)
	ds_write_b128 v172, v[200:203] offset:9216
	s_waitcnt vmcnt(12)
	ds_write_b128 v172, v[204:207] offset:13824
	s_waitcnt vmcnt(11)
	ds_write_b128 v172, v[208:211] offset:18432
	s_waitcnt vmcnt(10)
	ds_write_b128 v172, v[212:215] offset:23040
	s_waitcnt vmcnt(9)
	ds_write_b128 v172, v[216:219] offset:27648
	s_waitcnt vmcnt(8)
	ds_write_b128 v172, v[220:223] offset:32256
	global_load_dwordx4 v[192:195], v[228:229], off offset:640
	global_load_dwordx4 v[196:199], v[230:231], off offset:640
	global_load_dwordx4 v[200:203], v[232:233], off offset:640
	global_load_dwordx4 v[204:207], v[234:235], off offset:640
	global_load_dwordx4 v[208:211], v[238:239], off offset:640
	global_load_dwordx4 v[212:215], v[240:241], off offset:640
	global_load_dwordx4 v[216:219], v[242:243], off offset:640
	global_load_dwordx4 v[220:223], v[244:245], off offset:640
	s_waitcnt lgkmcnt(0)
	s_barrier
	ds_read_b128 v[66:69], v162
	ds_read_b128 v[70:73], v163 offset:18432
	ds_read_b128 v[74:77], v162 offset:32
	ds_read_b128 v[78:81], v163 offset:18464
	ds_read_b128 v[82:85], v171 offset:18432
	ds_read_b128 v[174:177], v163 offset:23136
	s_waitcnt lgkmcnt(4)
	v_mfma_f32_32x32x16_f16 v[50:65], v[66:69], v[70:73], v[50:65]
	s_waitcnt lgkmcnt(1)
	v_mfma_f32_32x32x16_f16 v[34:49], v[66:69], v[82:85], v[34:49]
	ds_read_b128 v[66:69], v162 offset:4608
	ds_read_b128 v[86:89], v162 offset:4640
	s_waitcnt lgkmcnt(1)
	v_mfma_f32_32x32x16_f16 v[18:33], v[66:69], v[70:73], v[18:33]
	v_mfma_f32_32x32x16_f16 v[2:17], v[66:69], v[82:85], v[2:17]
	ds_read_b128 v[66:69], v163 offset:23072
	ds_read_b128 v[70:73], v163 offset:23104
	v_mfma_f32_32x32x16_f16 v[50:65], v[74:77], v[78:81], v[50:65]
	s_waitcnt lgkmcnt(1)
	v_mfma_f32_32x32x16_f16 v[34:49], v[74:77], v[66:69], v[34:49]
	v_mfma_f32_32x32x16_f16 v[18:33], v[86:89], v[78:81], v[18:33]
	v_mfma_f32_32x32x16_f16 v[2:17], v[86:89], v[66:69], v[2:17]
	ds_read_b128 v[66:69], v162 offset:64
	ds_read_b128 v[74:77], v163 offset:18496
	ds_read_b128 v[78:81], v162 offset:96
	ds_read_b128 v[82:85], v163 offset:18528
	ds_read_b128 v[86:89], v162 offset:4672
	ds_read_b128 v[178:181], v162 offset:4704
	s_waitcnt lgkmcnt(4)
	v_mfma_f32_32x32x16_f16 v[50:65], v[66:69], v[74:77], v[50:65]
	v_mfma_f32_32x32x16_f16 v[34:49], v[66:69], v[70:73], v[34:49]
	s_waitcnt lgkmcnt(1)
	v_mfma_f32_32x32x16_f16 v[18:33], v[86:89], v[74:77], v[18:33]
	v_mfma_f32_32x32x16_f16 v[2:17], v[86:89], v[70:73], v[2:17]
	v_mfma_f32_32x32x16_f16 v[50:65], v[78:81], v[82:85], v[50:65]
	v_mfma_f32_32x32x16_f16 v[34:49], v[78:81], v[174:177], v[34:49]
	s_waitcnt lgkmcnt(0)
	v_mfma_f32_32x32x16_f16 v[18:33], v[178:181], v[82:85], v[18:33]
	v_mfma_f32_32x32x16_f16 v[2:17], v[178:181], v[174:177], v[2:17]
	s_barrier
	s_waitcnt vmcnt(15)
	ds_write_b128 v172, v[130:133]
	s_waitcnt vmcnt(14)
	ds_write_b128 v172, v[134:137] offset:4608
	s_waitcnt vmcnt(13)
	ds_write_b128 v172, v[138:141] offset:9216
	s_waitcnt vmcnt(12)
	ds_write_b128 v172, v[142:145] offset:13824
	s_waitcnt vmcnt(11)
	ds_write_b128 v172, v[146:149] offset:18432
	s_waitcnt vmcnt(10)
	ds_write_b128 v172, v[150:153] offset:23040
	s_waitcnt vmcnt(9)
	ds_write_b128 v172, v[154:157] offset:27648
	s_waitcnt vmcnt(8)
	ds_write_b128 v172, v[158:161] offset:32256
	global_load_dwordx4 v[130:133], v[228:229], off offset:768
	global_load_dwordx4 v[134:137], v[230:231], off offset:768
	global_load_dwordx4 v[138:141], v[232:233], off offset:768
	global_load_dwordx4 v[142:145], v[234:235], off offset:768
	global_load_dwordx4 v[146:149], v[238:239], off offset:768
	global_load_dwordx4 v[150:153], v[240:241], off offset:768
	global_load_dwordx4 v[154:157], v[242:243], off offset:768
	global_load_dwordx4 v[158:161], v[244:245], off offset:768
	s_waitcnt lgkmcnt(0)
	s_barrier
	ds_read_b128 v[66:69], v162
	ds_read_b128 v[70:73], v163 offset:18432
	ds_read_b128 v[74:77], v162 offset:32
	ds_read_b128 v[78:81], v163 offset:18464
	ds_read_b128 v[82:85], v171 offset:18432
	ds_read_b128 v[174:177], v163 offset:23136
	s_waitcnt lgkmcnt(4)
	v_mfma_f32_32x32x16_f16 v[50:65], v[66:69], v[70:73], v[50:65]
	s_waitcnt lgkmcnt(1)
	v_mfma_f32_32x32x16_f16 v[34:49], v[66:69], v[82:85], v[34:49]
	ds_read_b128 v[66:69], v162 offset:4608
	ds_read_b128 v[86:89], v162 offset:4640
	s_waitcnt lgkmcnt(1)
	v_mfma_f32_32x32x16_f16 v[18:33], v[66:69], v[70:73], v[18:33]
	v_mfma_f32_32x32x16_f16 v[2:17], v[66:69], v[82:85], v[2:17]
	ds_read_b128 v[66:69], v163 offset:23072
	ds_read_b128 v[70:73], v163 offset:23104
	v_mfma_f32_32x32x16_f16 v[50:65], v[74:77], v[78:81], v[50:65]
	s_waitcnt lgkmcnt(1)
	v_mfma_f32_32x32x16_f16 v[34:49], v[74:77], v[66:69], v[34:49]
	v_mfma_f32_32x32x16_f16 v[18:33], v[86:89], v[78:81], v[18:33]
	v_mfma_f32_32x32x16_f16 v[2:17], v[86:89], v[66:69], v[2:17]
	ds_read_b128 v[66:69], v162 offset:64
	ds_read_b128 v[74:77], v163 offset:18496
	ds_read_b128 v[78:81], v162 offset:96
	ds_read_b128 v[82:85], v163 offset:18528
	ds_read_b128 v[86:89], v162 offset:4672
	ds_read_b128 v[178:181], v162 offset:4704
	s_waitcnt lgkmcnt(4)
	v_mfma_f32_32x32x16_f16 v[50:65], v[66:69], v[74:77], v[50:65]
	v_mfma_f32_32x32x16_f16 v[34:49], v[66:69], v[70:73], v[34:49]
	s_waitcnt lgkmcnt(1)
	v_mfma_f32_32x32x16_f16 v[18:33], v[86:89], v[74:77], v[18:33]
	v_mfma_f32_32x32x16_f16 v[2:17], v[86:89], v[70:73], v[2:17]
	v_mfma_f32_32x32x16_f16 v[50:65], v[78:81], v[82:85], v[50:65]
	v_mfma_f32_32x32x16_f16 v[34:49], v[78:81], v[174:177], v[34:49]
	s_waitcnt lgkmcnt(0)
	v_mfma_f32_32x32x16_f16 v[18:33], v[178:181], v[82:85], v[18:33]
	v_mfma_f32_32x32x16_f16 v[2:17], v[178:181], v[174:177], v[2:17]
	s_barrier
; __device__ __forceinline__ float sigmoidf_(float x) { return 1.f / (1.f + __expf(-x)); }
; template <int NI, class LA, class LB, class EP>
; __device__ __forceinline__ void gemm_tile(int K, LA loadA, LB loadB, EP epi, char* smem) {
;     ...
;   for (int kt = 0; kt < nk; ++kt) {
;     __syncthreads();
; #pragma unroll
;     for (int i = 0; i < 4; ++i) *(uint4*)&sA[(lr + 32 * i) * 72 + lc] = ra[i];
; #pragma unroll
;     for (int i = 0; i < NB; ++i) *(uint4*)&sB[(lr + 32 * i) * 72 + lc] = rb[i];
;     __syncthreads();
;     if (kt + 1 < nk) {
;       const int kk = (kt + 1) * 64 + lc;
; #pragma unroll
;       for (int i = 0; i < 4; ++i) ra[i] = loadA(lr + 32 * i, kk);
; #pragma unroll
;       for (int i = 0; i < NB; ++i) rb[i] = loadB(lr + 32 * i, kk);
;     }
; #pragma unroll
;     for (int s = 0; s < 4; ++s) {
;       h8 af[2], bf[NI];
; #pragma unroll
;       for (int mi = 0; mi < 2; ++mi)
;         af[mi] = *(const h8*)&sA[(wm * 64 + mi * 32 + (lane & 31)) * 72 + s * 16 + (lane >> 5) * 8];
; #pragma unroll
;       for (int ni = 0; ni < NI; ++ni)
;         bf[ni] = *(const h8*)&sB[(wn * (NI * 32) + ni * 32 + (lane & 31)) * 72 + s * 16 + (lane >> 5) * 8];
; #pragma unroll
;       for (int mi = 0; mi < 2; ++mi)
; #pragma unroll
;         for (int ni = 0; ni < NI; ++ni)
;           acc[mi][ni] = __builtin_amdgcn_mfma_f32_32x32x16_f16(af[mi], bf[ni], acc[mi][ni], 0, 0, 0);
;     }
; __device__ __forceinline__ void phase_merge(const KP& p, char* smem, int* q, int xcc) {
;     ...
;           [&](int mi, int ni, int r, int row, int col, float v) {
;             const float gz = (float)G[(size_t)row * NU + col];
;             tot[mi][ni][r] += sigmoidf_(gz) * v;
;           },
	s_waitcnt vmcnt(15)
	ds_write_b128 v172, v[192:195]
	s_waitcnt vmcnt(14)
	ds_write_b128 v172, v[196:199] offset:4608
	s_waitcnt vmcnt(13)
	ds_write_b128 v172, v[200:203] offset:9216
	s_waitcnt vmcnt(12)
	ds_write_b128 v172, v[204:207] offset:13824
	s_waitcnt vmcnt(11)
	ds_write_b128 v172, v[208:211] offset:18432
	s_waitcnt vmcnt(10)
	ds_write_b128 v172, v[212:215] offset:23040
	s_waitcnt vmcnt(9)
	ds_write_b128 v172, v[216:219] offset:27648
	s_waitcnt vmcnt(8)
	ds_write_b128 v172, v[220:223] offset:32256
	s_waitcnt lgkmcnt(0)
	s_barrier
	ds_read_b128 v[66:69], v162
	ds_read_b128 v[70:73], v163 offset:18432
	ds_read_b128 v[74:77], v162 offset:32
	ds_read_b128 v[78:81], v163 offset:18464
	ds_read_b128 v[82:85], v171 offset:18432
	ds_read_b128 v[174:177], v163 offset:23136
	s_waitcnt lgkmcnt(4)
	v_mfma_f32_32x32x16_f16 v[50:65], v[66:69], v[70:73], v[50:65]
	s_waitcnt lgkmcnt(1)
	v_mfma_f32_32x32x16_f16 v[34:49], v[66:69], v[82:85], v[34:49]
	ds_read_b128 v[66:69], v162 offset:4608
	ds_read_b128 v[86:89], v162 offset:4640
	s_waitcnt lgkmcnt(1)
	v_mfma_f32_32x32x16_f16 v[18:33], v[66:69], v[70:73], v[18:33]
	v_mfma_f32_32x32x16_f16 v[2:17], v[66:69], v[82:85], v[2:17]
	ds_read_b128 v[66:69], v163 offset:23072
	ds_read_b128 v[70:73], v163 offset:23104
	v_mfma_f32_32x32x16_f16 v[50:65], v[74:77], v[78:81], v[50:65]
	s_waitcnt lgkmcnt(1)
	v_mfma_f32_32x32x16_f16 v[34:49], v[74:77], v[66:69], v[34:49]
	v_mfma_f32_32x32x16_f16 v[18:33], v[86:89], v[78:81], v[18:33]
	v_mfma_f32_32x32x16_f16 v[2:17], v[86:89], v[66:69], v[2:17]
	ds_read_b128 v[66:69], v162 offset:64
	ds_read_b128 v[74:77], v163 offset:18496
	ds_read_b128 v[78:81], v162 offset:96
	ds_read_b128 v[82:85], v163 offset:18528
	ds_read_b128 v[86:89], v162 offset:4672
	ds_read_b128 v[178:181], v162 offset:4704
	s_waitcnt lgkmcnt(4)
	v_mfma_f32_32x32x16_f16 v[50:65], v[66:69], v[74:77], v[50:65]
	v_mfma_f32_32x32x16_f16 v[34:49], v[66:69], v[70:73], v[34:49]
	s_waitcnt lgkmcnt(1)
	v_mfma_f32_32x32x16_f16 v[18:33], v[86:89], v[74:77], v[18:33]
	v_mfma_f32_32x32x16_f16 v[2:17], v[86:89], v[70:73], v[2:17]
	v_mfma_f32_32x32x16_f16 v[50:65], v[78:81], v[82:85], v[50:65]
	v_mfma_f32_32x32x16_f16 v[34:49], v[78:81], v[174:177], v[34:49]
	s_waitcnt lgkmcnt(0)
	v_mfma_f32_32x32x16_f16 v[18:33], v[178:181], v[82:85], v[18:33]
	v_mfma_f32_32x32x16_f16 v[2:17], v[178:181], v[174:177], v[2:17]
	s_barrier
	s_waitcnt vmcnt(7)
	ds_write_b128 v172, v[130:133]
	s_waitcnt vmcnt(6)
	ds_write_b128 v172, v[134:137] offset:4608
	s_waitcnt vmcnt(5)
	ds_write_b128 v172, v[138:141] offset:9216
	s_waitcnt vmcnt(4)
	ds_write_b128 v172, v[142:145] offset:13824
	s_waitcnt vmcnt(3)
	ds_write_b128 v172, v[146:149] offset:18432
	s_waitcnt vmcnt(2)
	ds_write_b128 v172, v[150:153] offset:23040
	s_waitcnt vmcnt(1)
	ds_write_b128 v172, v[154:157] offset:27648
	s_waitcnt vmcnt(0)
	ds_write_b128 v172, v[158:161] offset:32256
	s_waitcnt lgkmcnt(0)
	s_barrier
	ds_read_b128 v[66:69], v162 offset:4608
	ds_read_b128 v[70:73], v171 offset:18432
	ds_read_b128 v[74:77], v162
	ds_read_b128 v[78:81], v162 offset:32
	ds_read_b128 v[82:85], v163 offset:18432
	ds_read_b128 v[86:89], v163 offset:18464
	s_waitcnt lgkmcnt(1)
	v_mfma_f32_32x32x16_f16 v[50:65], v[74:77], v[82:85], v[50:65]
	s_lshl_b32 s2, s56, 11
	s_add_u32 s2, s52, s2
	s_addc_u32 s3, s53, 0
	v_lshlrev_b32_e32 v0, 1, v0
	s_add_i32 s56, s56, 1
	s_add_u32 s38, s38, 0x100000
	s_addc_u32 s39, s39, 0
	v_mfma_f32_32x32x16_f16 v[34:49], v[74:77], v[70:73], v[34:49]
	s_cmp_lg_u32 s56, 3
	v_mfma_f32_32x32x16_f16 v[18:33], v[66:69], v[82:85], v[18:33]
	v_mfma_f32_32x32x16_f16 v[2:17], v[66:69], v[70:73], v[2:17]
	ds_read_b128 v[66:69], v162 offset:4640
	ds_read_b128 v[70:73], v163 offset:23072
	s_waitcnt lgkmcnt(2)
	v_mfma_f32_32x32x16_f16 v[50:65], v[78:81], v[86:89], v[50:65]
	s_waitcnt lgkmcnt(0)
	v_mfma_f32_32x32x16_f16 v[34:49], v[78:81], v[70:73], v[34:49]
	v_mfma_f32_32x32x16_f16 v[18:33], v[66:69], v[86:89], v[18:33]
	v_mfma_f32_32x32x16_f16 v[2:17], v[66:69], v[70:73], v[2:17]
	ds_read_b128 v[66:69], v162 offset:64
	ds_read_b128 v[70:73], v162 offset:4672
	ds_read_b128 v[74:77], v163 offset:18496
	ds_read_b128 v[78:81], v163 offset:23104
	s_waitcnt lgkmcnt(1)
	v_mfma_f32_32x32x16_f16 v[50:65], v[66:69], v[74:77], v[50:65]
	s_waitcnt lgkmcnt(0)
	v_mfma_f32_32x32x16_f16 v[34:49], v[66:69], v[78:81], v[34:49]
	v_mfma_f32_32x32x16_f16 v[18:33], v[70:73], v[74:77], v[18:33]
	v_mfma_f32_32x32x16_f16 v[2:17], v[70:73], v[78:81], v[2:17]
	ds_read_b128 v[66:69], v162 offset:96
	ds_read_b128 v[70:73], v162 offset:4704
	ds_read_b128 v[74:77], v163 offset:18528
	ds_read_b128 v[78:81], v163 offset:23136
	s_waitcnt lgkmcnt(1)
	v_mfma_f32_32x32x16_f16 v[50:65], v[66:69], v[74:77], v[50:65]
	s_waitcnt lgkmcnt(0)
	v_mfma_f32_32x32x16_f16 v[34:49], v[66:69], v[78:81], v[34:49]
	v_mfma_f32_32x32x16_f16 v[18:33], v[70:73], v[74:77], v[18:33]
	v_mfma_f32_32x32x16_f16 v[2:17], v[70:73], v[78:81], v[2:17]
	v_mov_b32_e32 v228, 0x11fe4
	v_mov_b32_e32 v229, 0x100
	v_mov_b32_e32 v230, 2
	v_mov_b32_e32 v231, 0x3727c5ac
	v_mov_b32_e32 v232, 0x11fa0
	v_mov_b32_e32 v233, 0x80000
	v_mov_b32_e32 v234, 0x1d0000
	v_mov_b32_e32 v235, 0xa800
	v_mov_b32_e32 v238, 0x4000
	v_mov_b32_e32 v239, 0x4400
	v_mov_b32_e32 v240, 0x4800
	v_mov_b32_e32 v241, 0x4c00
	v_mov_b32_e32 v242, 0xf149f2ca
	v_mov_b32_e32 v243, 0x200
	v_mov_b32_e32 v244, 0x400
	v_mov_b32_e32 v245, 0x600
	ds_read_b128 v[130:133], v90
	ds_read_b128 v[134:137], v90 offset:4096
	ds_read_b128 v[138:141], v90 offset:8192
	ds_read_b128 v[142:145], v90 offset:12288
	ds_read_b128 v[146:149], v90 offset:16384
	ds_read_b128 v[150:153], v90 offset:20480
	ds_read_b128 v[154:157], v90 offset:24576
	ds_read_b128 v[158:161], v90 offset:28672
	s_waitcnt lgkmcnt(0)
; __device__ __forceinline__ float sigmoidf_(float x) { return 1.f / (1.f + __expf(-x)); }
; __device__ __forceinline__ void phase_merge(const KP& p, char* smem, int* q, int xcc) {
;     ...
;           [&](int mi, int ni, int r, int row, int col, float v) {
;             const float gz = (float)G[(size_t)row * NU + col];
;             tot[mi][ni][r] += sigmoidf_(gz) * v;
;           },
	v_lshrrev_b32_e32 v94, 7, v224
	v_lshlrev_b32_e32 v94, 4, v94
	v_bfe_u32 v95, v224, 5, 1
	v_add_u32_e32 v94, v94, v95
	v_mul_u32_u24_e32 v94, 0xe800, v94
	v_bfe_u32 v95, v224, 6, 1
	v_lshl_add_u32 v94, v95, 7, v94
	v_and_b32_e32 v95, 31, v224
	v_lshl_add_u32 v94, v95, 1, v94
	s_mov_b64 s[40:41], s[2:3]
	v_mov_b32_e32 v96, v94
	global_load_ushort v192, v96, s[40:41]
	v_add_u32_e32 v96, 0x3a00, v94
	global_load_ushort v193, v96, s[40:41]
	v_add_u32_e32 v96, 0x7400, v94
	global_load_ushort v194, v96, s[40:41]
	v_add_u32_e32 v96, 0xae00, v94
	global_load_ushort v195, v96, s[40:41]
	v_add_u32_e32 v96, 0x1d000, v94
	global_load_ushort v196, v96, s[40:41]
	v_add_u32_e32 v96, 0x20a00, v94
	global_load_ushort v197, v96, s[40:41]
	v_add_u32_e32 v96, 0x24400, v94
	global_load_ushort v198, v96, s[40:41]
	v_add_u32_e32 v96, 0x27e00, v94
	global_load_ushort v199, v96, s[40:41]
	v_add_u32_e32 v96, 0x3a000, v94
	global_load_ushort v200, v96, s[40:41]
	v_add_u32_e32 v96, 0x3da00, v94
	global_load_ushort v201, v96, s[40:41]
	v_add_u32_e32 v96, 0x41400, v94
	global_load_ushort v202, v96, s[40:41]
	v_add_u32_e32 v96, 0x44e00, v94
	global_load_ushort v203, v96, s[40:41]
	v_add_u32_e32 v96, 0x57000, v94
	global_load_ushort v204, v96, s[40:41]
	v_add_u32_e32 v96, 0x5aa00, v94
	global_load_ushort v205, v96, s[40:41]
	v_add_u32_e32 v96, 0x5e400, v94
	global_load_ushort v206, v96, s[40:41]
	v_add_u32_e32 v96, 0x61e00, v94
	global_load_ushort v207, v96, s[40:41]
	v_mov_b32_e32 v96, v94
	global_load_ushort v208, v96, s[40:41] offset:64
	v_add_u32_e32 v96, 0x3a00, v94
	global_load_ushort v209, v96, s[40:41] offset:64
	v_add_u32_e32 v96, 0x7400, v94
	global_load_ushort v210, v96, s[40:41] offset:64
	v_add_u32_e32 v96, 0xae00, v94
	global_load_ushort v211, v96, s[40:41] offset:64
	v_add_u32_e32 v96, 0x1d000, v94
	global_load_ushort v212, v96, s[40:41] offset:64
	v_add_u32_e32 v96, 0x20a00, v94
	global_load_ushort v213, v96, s[40:41] offset:64
	v_add_u32_e32 v96, 0x24400, v94
	global_load_ushort v214, v96, s[40:41] offset:64
	v_add_u32_e32 v96, 0x27e00, v94
	global_load_ushort v215, v96, s[40:41] offset:64
	v_add_u32_e32 v96, 0x3a000, v94
	global_load_ushort v216, v96, s[40:41] offset:64
	v_add_u32_e32 v96, 0x3da00, v94
	global_load_ushort v217, v96, s[40:41] offset:64
	v_add_u32_e32 v96, 0x41400, v94
	global_load_ushort v218, v96, s[40:41] offset:64
	v_add_u32_e32 v96, 0x44e00, v94
	global_load_ushort v219, v96, s[40:41] offset:64
	v_add_u32_e32 v96, 0x57000, v94
	global_load_ushort v220, v96, s[40:41] offset:64
	v_add_u32_e32 v96, 0x5aa00, v94
	global_load_ushort v221, v96, s[40:41] offset:64
	v_add_u32_e32 v96, 0x5e400, v94
	global_load_ushort v222, v96, s[40:41] offset:64
	v_add_u32_e32 v96, 0x61e00, v94
	global_load_ushort v223, v96, s[40:41] offset:64
	s_nop 7
	s_waitcnt vmcnt(30)
	v_cvt_f32_f16_e32 v68, v192
	v_cvt_f32_f16_e32 v69, v193
	v_add_u32_e32 v96, 0x74000, v94
	global_load_ushort v192, v96, s[40:41]
	v_add_u32_e32 v96, 0x77a00, v94
	global_load_ushort v193, v96, s[40:41]
	v_mul_f32_e32 v68, 0xbfb8aa3b, v68
	v_mul_f32_e32 v69, 0xbfb8aa3b, v69
	v_exp_f32_e32 v68, v68
	v_exp_f32_e32 v69, v69
	s_nop 0
	v_pk_add_f32 v[68:69], v[68:69], 1.0 op_sel_hi:[1,0]
	s_nop 0
	v_div_scale_f32 v70, s[2:3], v69, v69, 1.0
	v_rcp_f32_e32 v71, v70
	s_nop 0
	v_fma_f32 v72, -v70, v71, 1.0
	v_fmac_f32_e32 v71, v72, v71
	v_div_scale_f32 v72, vcc, 1.0, v69, 1.0
	v_mul_f32_e32 v73, v72, v71
	v_fma_f32 v74, -v70, v73, v72
	v_fmac_f32_e32 v73, v74, v71
	v_fma_f32 v70, -v70, v73, v72
	v_div_fmas_f32 v70, v70, v71, v73
	v_div_fixup_f32 v69, v70, v69, 1.0
	v_div_scale_f32 v70, s[2:3], v68, v68, 1.0
	v_rcp_f32_e32 v71, v70
	s_nop 0
	v_fma_f32 v72, -v70, v71, 1.0
	v_fmac_f32_e32 v71, v72, v71
	v_div_scale_f32 v72, vcc, 1.0, v68, 1.0
	v_mul_f32_e32 v73, v72, v71
	v_fma_f32 v74, -v70, v73, v72
	v_fmac_f32_e32 v73, v74, v71
	v_fma_f32 v70, -v70, v73, v72
	v_div_fmas_f32 v70, v70, v71, v73
	v_div_fixup_f32 v68, v70, v68, 1.0
	v_pk_fma_f32 v[160:161], v[50:51], v[68:69], v[160:161]
	s_waitcnt vmcnt(30)
	v_cvt_f32_f16_e32 v68, v194
	v_cvt_f32_f16_e32 v69, v195
	v_add_u32_e32 v96, 0x7b400, v94
	global_load_ushort v194, v96, s[40:41]
	v_add_u32_e32 v96, 0x7ee00, v94
	global_load_ushort v195, v96, s[40:41]
	v_mul_f32_e32 v68, 0xbfb8aa3b, v68
	v_mul_f32_e32 v69, 0xbfb8aa3b, v69
	v_exp_f32_e32 v68, v68
	v_exp_f32_e32 v69, v69
	s_nop 0
	v_pk_add_f32 v[68:69], v[68:69], 1.0 op_sel_hi:[1,0]
	s_nop 0
	v_div_scale_f32 v70, s[2:3], v69, v69, 1.0
	v_rcp_f32_e32 v71, v70
	s_nop 0
	v_fma_f32 v72, -v70, v71, 1.0
	v_fmac_f32_e32 v71, v72, v71
	v_div_scale_f32 v72, vcc, 1.0, v69, 1.0
	v_mul_f32_e32 v73, v72, v71
	v_fma_f32 v74, -v70, v73, v72
	v_fmac_f32_e32 v73, v74, v71
	v_fma_f32 v70, -v70, v73, v72
	v_div_fmas_f32 v70, v70, v71, v73
	v_div_fixup_f32 v69, v70, v69, 1.0
	v_div_scale_f32 v70, s[2:3], v68, v68, 1.0
	v_rcp_f32_e32 v71, v70
	s_nop 0
	v_fma_f32 v72, -v70, v71, 1.0
	v_fmac_f32_e32 v71, v72, v71
	v_div_scale_f32 v72, vcc, 1.0, v68, 1.0
	v_mul_f32_e32 v73, v72, v71
	v_fma_f32 v74, -v70, v73, v72
	v_fmac_f32_e32 v73, v74, v71
	v_fma_f32 v70, -v70, v73, v72
	v_div_fmas_f32 v70, v70, v71, v73
	v_div_fixup_f32 v68, v70, v68, 1.0
	v_pk_fma_f32 v[158:159], v[52:53], v[68:69], v[158:159]
	s_waitcnt vmcnt(30)
; __device__ __forceinline__ float sigmoidf_(float x) { return 1.f / (1.f + __expf(-x)); }
; __device__ __forceinline__ void phase_merge(const KP& p, char* smem, int* q, int xcc) {
;     ...
;           [&](int mi, int ni, int r, int row, int col, float v) {
;             const float gz = (float)G[(size_t)row * NU + col];
;             tot[mi][ni][r] += sigmoidf_(gz) * v;
;           },
	v_cvt_f32_f16_e32 v68, v196
	v_cvt_f32_f16_e32 v69, v197
	v_add_u32_e32 v96, 0x91000, v94
	global_load_ushort v196, v96, s[40:41]
	v_add_u32_e32 v96, 0x94a00, v94
	global_load_ushort v197, v96, s[40:41]
	v_mul_f32_e32 v68, 0xbfb8aa3b, v68
	v_mul_f32_e32 v69, 0xbfb8aa3b, v69
	v_exp_f32_e32 v68, v68
	v_exp_f32_e32 v69, v69
	s_nop 0
	v_pk_add_f32 v[68:69], v[68:69], 1.0 op_sel_hi:[1,0]
	s_nop 0
	v_div_scale_f32 v70, s[2:3], v69, v69, 1.0
	v_rcp_f32_e32 v71, v70
	s_nop 0
	v_fma_f32 v72, -v70, v71, 1.0
	v_fmac_f32_e32 v71, v72, v71
	v_div_scale_f32 v72, vcc, 1.0, v69, 1.0
	v_mul_f32_e32 v73, v72, v71
	v_fma_f32 v74, -v70, v73, v72
	v_fmac_f32_e32 v73, v74, v71
	v_fma_f32 v70, -v70, v73, v72
	v_div_fmas_f32 v70, v70, v71, v73
	v_div_fixup_f32 v69, v70, v69, 1.0
	v_div_scale_f32 v70, s[2:3], v68, v68, 1.0
	v_rcp_f32_e32 v71, v70
	s_nop 0
	v_fma_f32 v72, -v70, v71, 1.0
	v_fmac_f32_e32 v71, v72, v71
	v_div_scale_f32 v72, vcc, 1.0, v68, 1.0
	v_mul_f32_e32 v73, v72, v71
	v_fma_f32 v74, -v70, v73, v72
	v_fmac_f32_e32 v73, v74, v71
	v_fma_f32 v70, -v70, v73, v72
	v_div_fmas_f32 v70, v70, v71, v73
	v_div_fixup_f32 v68, v70, v68, 1.0
	v_pk_fma_f32 v[156:157], v[54:55], v[68:69], v[156:157]
	s_waitcnt vmcnt(30)
	v_cvt_f32_f16_e32 v68, v198
	v_cvt_f32_f16_e32 v69, v199
	v_add_u32_e32 v96, 0x98400, v94
	global_load_ushort v198, v96, s[40:41]
	v_add_u32_e32 v96, 0x9be00, v94
	global_load_ushort v199, v96, s[40:41]
	v_mul_f32_e32 v68, 0xbfb8aa3b, v68
	v_mul_f32_e32 v69, 0xbfb8aa3b, v69
	v_exp_f32_e32 v68, v68
	v_exp_f32_e32 v69, v69
	s_nop 0
	v_pk_add_f32 v[68:69], v[68:69], 1.0 op_sel_hi:[1,0]
	s_nop 0
	v_div_scale_f32 v70, s[2:3], v69, v69, 1.0
	v_rcp_f32_e32 v71, v70
	s_nop 0
	v_fma_f32 v72, -v70, v71, 1.0
	v_fmac_f32_e32 v71, v72, v71
	v_div_scale_f32 v72, vcc, 1.0, v69, 1.0
	v_mul_f32_e32 v73, v72, v71
	v_fma_f32 v74, -v70, v73, v72
	v_fmac_f32_e32 v73, v74, v71
	v_fma_f32 v70, -v70, v73, v72
	v_div_fmas_f32 v70, v70, v71, v73
	v_div_fixup_f32 v69, v70, v69, 1.0
	v_div_scale_f32 v70, s[2:3], v68, v68, 1.0
	v_rcp_f32_e32 v71, v70
	s_nop 0
	v_fma_f32 v72, -v70, v71, 1.0
	v_fmac_f32_e32 v71, v72, v71
	v_div_scale_f32 v72, vcc, 1.0, v68, 1.0
	v_mul_f32_e32 v73, v72, v71
	v_fma_f32 v74, -v70, v73, v72
	v_fmac_f32_e32 v73, v74, v71
	v_fma_f32 v70, -v70, v73, v72
	v_div_fmas_f32 v70, v70, v71, v73
	v_div_fixup_f32 v68, v70, v68, 1.0
	v_pk_fma_f32 v[154:155], v[56:57], v[68:69], v[154:155]
	s_waitcnt vmcnt(30)
	v_cvt_f32_f16_e32 v68, v200
	v_cvt_f32_f16_e32 v69, v201
	v_add_u32_e32 v96, 0xae000, v94
	global_load_ushort v200, v96, s[40:41]
	v_add_u32_e32 v96, 0xb1a00, v94
	global_load_ushort v201, v96, s[40:41]
	v_mul_f32_e32 v68, 0xbfb8aa3b, v68
	v_mul_f32_e32 v69, 0xbfb8aa3b, v69
	v_exp_f32_e32 v68, v68
	v_exp_f32_e32 v69, v69
	s_nop 0
	v_pk_add_f32 v[68:69], v[68:69], 1.0 op_sel_hi:[1,0]
	s_nop 0
	v_div_scale_f32 v70, s[2:3], v69, v69, 1.0
	v_rcp_f32_e32 v71, v70
	s_nop 0
	v_fma_f32 v72, -v70, v71, 1.0
	v_fmac_f32_e32 v71, v72, v71
	v_div_scale_f32 v72, vcc, 1.0, v69, 1.0
	v_mul_f32_e32 v73, v72, v71
	v_fma_f32 v74, -v70, v73, v72
	v_fmac_f32_e32 v73, v74, v71
	v_fma_f32 v70, -v70, v73, v72
	v_div_fmas_f32 v70, v70, v71, v73
	v_div_fixup_f32 v69, v70, v69, 1.0
	v_div_scale_f32 v70, s[2:3], v68, v68, 1.0
	v_rcp_f32_e32 v71, v70
	s_nop 0
	v_fma_f32 v72, -v70, v71, 1.0
	v_fmac_f32_e32 v71, v72, v71
	v_div_scale_f32 v72, vcc, 1.0, v68, 1.0
	v_mul_f32_e32 v73, v72, v71
	v_fma_f32 v74, -v70, v73, v72
	v_fmac_f32_e32 v73, v74, v71
	v_fma_f32 v70, -v70, v73, v72
	v_div_fmas_f32 v70, v70, v71, v73
	v_div_fixup_f32 v68, v70, v68, 1.0
	v_pk_fma_f32 v[152:153], v[58:59], v[68:69], v[152:153]
	s_waitcnt vmcnt(30)
	v_cvt_f32_f16_e32 v68, v202
	v_cvt_f32_f16_e32 v69, v203
	v_add_u32_e32 v96, 0xb5400, v94
	global_load_ushort v202, v96, s[40:41]
	v_add_u32_e32 v96, 0xb8e00, v94
	global_load_ushort v203, v96, s[40:41]
	v_mul_f32_e32 v68, 0xbfb8aa3b, v68
	v_mul_f32_e32 v69, 0xbfb8aa3b, v69
	v_exp_f32_e32 v68, v68
	v_exp_f32_e32 v69, v69
	s_nop 0
	v_pk_add_f32 v[68:69], v[68:69], 1.0 op_sel_hi:[1,0]
	s_nop 0
	v_div_scale_f32 v70, s[2:3], v69, v69, 1.0
	v_rcp_f32_e32 v71, v70
	s_nop 0
	v_fma_f32 v72, -v70, v71, 1.0
	v_fmac_f32_e32 v71, v72, v71
	v_div_scale_f32 v72, vcc, 1.0, v69, 1.0
	v_mul_f32_e32 v73, v72, v71
	v_fma_f32 v74, -v70, v73, v72
	v_fmac_f32_e32 v73, v74, v71
	v_fma_f32 v70, -v70, v73, v72
	v_div_fmas_f32 v70, v70, v71, v73
	v_div_fixup_f32 v69, v70, v69, 1.0
	v_div_scale_f32 v70, s[2:3], v68, v68, 1.0
	v_rcp_f32_e32 v71, v70
	s_nop 0
	v_fma_f32 v72, -v70, v71, 1.0
	v_fmac_f32_e32 v71, v72, v71
	v_div_scale_f32 v72, vcc, 1.0, v68, 1.0
	v_mul_f32_e32 v73, v72, v71
	v_fma_f32 v74, -v70, v73, v72
	v_fmac_f32_e32 v73, v74, v71
	v_fma_f32 v70, -v70, v73, v72
	v_div_fmas_f32 v70, v70, v71, v73
	v_div_fixup_f32 v68, v70, v68, 1.0
	v_pk_fma_f32 v[150:151], v[60:61], v[68:69], v[150:151]
	s_waitcnt vmcnt(30)
	v_cvt_f32_f16_e32 v68, v204
	v_cvt_f32_f16_e32 v69, v205
	v_add_u32_e32 v96, 0xcb000, v94
	global_load_ushort v204, v96, s[40:41]
	v_add_u32_e32 v96, 0xcea00, v94
	global_load_ushort v205, v96, s[40:41]
	v_mul_f32_e32 v68, 0xbfb8aa3b, v68
	v_mul_f32_e32 v69, 0xbfb8aa3b, v69
	v_exp_f32_e32 v68, v68
	v_exp_f32_e32 v69, v69
	s_nop 0
	v_pk_add_f32 v[68:69], v[68:69], 1.0 op_sel_hi:[1,0]
	s_nop 0
	v_div_scale_f32 v70, s[2:3], v69, v69, 1.0
	v_rcp_f32_e32 v71, v70
	s_nop 0
	v_fma_f32 v72, -v70, v71, 1.0
	v_fmac_f32_e32 v71, v72, v71
	v_div_scale_f32 v72, vcc, 1.0, v69, 1.0
	v_mul_f32_e32 v73, v72, v71
	v_fma_f32 v74, -v70, v73, v72
	v_fmac_f32_e32 v73, v74, v71
	v_fma_f32 v70, -v70, v73, v72
	v_div_fmas_f32 v70, v70, v71, v73
	v_div_fixup_f32 v69, v70, v69, 1.0
	v_div_scale_f32 v70, s[2:3], v68, v68, 1.0
	v_rcp_f32_e32 v71, v70
	s_nop 0
	v_fma_f32 v72, -v70, v71, 1.0
	v_fmac_f32_e32 v71, v72, v71
	v_div_scale_f32 v72, vcc, 1.0, v68, 1.0
	v_mul_f32_e32 v73, v72, v71
	v_fma_f32 v74, -v70, v73, v72
	v_fmac_f32_e32 v73, v74, v71
	v_fma_f32 v70, -v70, v73, v72
	v_div_fmas_f32 v70, v70, v71, v73
	v_div_fixup_f32 v68, v70, v68, 1.0
	v_pk_fma_f32 v[148:149], v[62:63], v[68:69], v[148:149]
	s_waitcnt vmcnt(30)
;   __device__ __forceinline__ const float* x() const { return (const float*)(const __attribute__((address_space(1))) float*)kp[0]; }
; __device__ __forceinline__ float sigmoidf_(float x) { return 1.f / (1.f + __expf(-x)); }
; __device__ __forceinline__ void phase_merge(const KP& p, char* smem, int* q, int xcc) {
;     ...
;           [&](int mi, int ni, int r, int row, int col, float v) {
;             const float gz = (float)G[(size_t)row * NU + col];
;             tot[mi][ni][r] += sigmoidf_(gz) * v;
;           },
	v_cvt_f32_f16_e32 v68, v206
	v_cvt_f32_f16_e32 v69, v207
	v_add_u32_e32 v96, 0xd2400, v94
	global_load_ushort v206, v96, s[40:41]
	v_add_u32_e32 v96, 0xd5e00, v94
	global_load_ushort v207, v96, s[40:41]
	v_mul_f32_e32 v68, 0xbfb8aa3b, v68
	v_mul_f32_e32 v69, 0xbfb8aa3b, v69
	v_exp_f32_e32 v68, v68
	v_exp_f32_e32 v69, v69
	s_nop 0
	v_pk_add_f32 v[68:69], v[68:69], 1.0 op_sel_hi:[1,0]
	s_nop 0
	v_div_scale_f32 v70, s[2:3], v69, v69, 1.0
	v_rcp_f32_e32 v71, v70
	s_nop 0
	v_fma_f32 v72, -v70, v71, 1.0
	v_fmac_f32_e32 v71, v72, v71
	v_div_scale_f32 v72, vcc, 1.0, v69, 1.0
	v_mul_f32_e32 v73, v72, v71
	v_fma_f32 v74, -v70, v73, v72
	v_fmac_f32_e32 v73, v74, v71
	v_fma_f32 v70, -v70, v73, v72
	v_div_fmas_f32 v70, v70, v71, v73
	v_div_fixup_f32 v69, v70, v69, 1.0
	v_div_scale_f32 v70, s[2:3], v68, v68, 1.0
	v_rcp_f32_e32 v71, v70
	s_nop 0
	v_fma_f32 v72, -v70, v71, 1.0
	v_fmac_f32_e32 v71, v72, v71
	v_div_scale_f32 v72, vcc, 1.0, v68, 1.0
	v_mul_f32_e32 v73, v72, v71
	v_fma_f32 v74, -v70, v73, v72
	v_fmac_f32_e32 v73, v74, v71
	v_fma_f32 v70, -v70, v73, v72
	v_div_fmas_f32 v70, v70, v71, v73
	v_div_fixup_f32 v68, v70, v68, 1.0
	v_pk_fma_f32 v[146:147], v[64:65], v[68:69], v[146:147]
	s_waitcnt vmcnt(30)
	v_cvt_f32_f16_e32 v68, v208
	v_cvt_f32_f16_e32 v69, v209
	v_add_u32_e32 v96, 0x74000, v94
	global_load_ushort v208, v96, s[40:41] offset:64
	v_add_u32_e32 v96, 0x77a00, v94
	global_load_ushort v209, v96, s[40:41] offset:64
	v_mul_f32_e32 v68, 0xbfb8aa3b, v68
	v_mul_f32_e32 v69, 0xbfb8aa3b, v69
	v_exp_f32_e32 v68, v68
	v_exp_f32_e32 v69, v69
	s_nop 0
	v_pk_add_f32 v[68:69], v[68:69], 1.0 op_sel_hi:[1,0]
	s_nop 0
	v_div_scale_f32 v70, s[2:3], v69, v69, 1.0
	v_rcp_f32_e32 v71, v70
	s_nop 0
	v_fma_f32 v72, -v70, v71, 1.0
	v_fmac_f32_e32 v71, v72, v71
	v_div_scale_f32 v72, vcc, 1.0, v69, 1.0
	v_mul_f32_e32 v73, v72, v71
	v_fma_f32 v74, -v70, v73, v72
	v_fmac_f32_e32 v73, v74, v71
	v_fma_f32 v70, -v70, v73, v72
	v_div_fmas_f32 v70, v70, v71, v73
	v_div_fixup_f32 v69, v70, v69, 1.0
	v_div_scale_f32 v70, s[2:3], v68, v68, 1.0
	v_rcp_f32_e32 v71, v70
	s_nop 0
	v_fma_f32 v72, -v70, v71, 1.0
	v_fmac_f32_e32 v71, v72, v71
	v_div_scale_f32 v72, vcc, 1.0, v68, 1.0
	v_mul_f32_e32 v73, v72, v71
	v_fma_f32 v74, -v70, v73, v72
	v_fmac_f32_e32 v73, v74, v71
	v_fma_f32 v70, -v70, v73, v72
	v_div_fmas_f32 v70, v70, v71, v73
	v_div_fixup_f32 v68, v70, v68, 1.0
	v_pk_fma_f32 v[144:145], v[34:35], v[68:69], v[144:145]
	s_waitcnt vmcnt(30)
	v_cvt_f32_f16_e32 v68, v210
	v_cvt_f32_f16_e32 v69, v211
	v_add_u32_e32 v96, 0x7b400, v94
	global_load_ushort v210, v96, s[40:41] offset:64
	v_add_u32_e32 v96, 0x7ee00, v94
	global_load_ushort v211, v96, s[40:41] offset:64
	v_mul_f32_e32 v68, 0xbfb8aa3b, v68
	v_mul_f32_e32 v69, 0xbfb8aa3b, v69
	v_exp_f32_e32 v68, v68
	v_exp_f32_e32 v69, v69
	s_nop 0
	v_pk_add_f32 v[68:69], v[68:69], 1.0 op_sel_hi:[1,0]
	s_nop 0
	v_div_scale_f32 v70, s[2:3], v69, v69, 1.0
	v_rcp_f32_e32 v71, v70
	s_nop 0
	v_fma_f32 v72, -v70, v71, 1.0
	v_fmac_f32_e32 v71, v72, v71
	v_div_scale_f32 v72, vcc, 1.0, v69, 1.0
	v_mul_f32_e32 v73, v72, v71
	v_fma_f32 v74, -v70, v73, v72
	v_fmac_f32_e32 v73, v74, v71
	v_fma_f32 v70, -v70, v73, v72
	v_div_fmas_f32 v70, v70, v71, v73
	v_div_fixup_f32 v69, v70, v69, 1.0
	v_div_scale_f32 v70, s[2:3], v68, v68, 1.0
	v_rcp_f32_e32 v71, v70
	s_nop 0
	v_fma_f32 v72, -v70, v71, 1.0
	v_fmac_f32_e32 v71, v72, v71
	v_div_scale_f32 v72, vcc, 1.0, v68, 1.0
	v_mul_f32_e32 v73, v72, v71
	v_fma_f32 v74, -v70, v73, v72
	v_fmac_f32_e32 v73, v74, v71
	v_fma_f32 v70, -v70, v73, v72
	v_div_fmas_f32 v70, v70, v71, v73
	v_div_fixup_f32 v68, v70, v68, 1.0
	v_pk_fma_f32 v[142:143], v[36:37], v[68:69], v[142:143]
	s_waitcnt vmcnt(30)
	v_cvt_f32_f16_e32 v68, v212
	v_cvt_f32_f16_e32 v69, v213
	v_add_u32_e32 v96, 0x91000, v94
	global_load_ushort v212, v96, s[40:41] offset:64
	v_add_u32_e32 v96, 0x94a00, v94
	global_load_ushort v213, v96, s[40:41] offset:64
	v_mul_f32_e32 v68, 0xbfb8aa3b, v68
	v_mul_f32_e32 v69, 0xbfb8aa3b, v69
	v_exp_f32_e32 v68, v68
	v_exp_f32_e32 v69, v69
	s_nop 0
	v_pk_add_f32 v[68:69], v[68:69], 1.0 op_sel_hi:[1,0]
	s_nop 0
	v_div_scale_f32 v70, s[2:3], v69, v69, 1.0
	v_rcp_f32_e32 v71, v70
	s_nop 0
	v_fma_f32 v72, -v70, v71, 1.0
	v_fmac_f32_e32 v71, v72, v71
	v_div_scale_f32 v72, vcc, 1.0, v69, 1.0
	v_mul_f32_e32 v73, v72, v71
	v_fma_f32 v74, -v70, v73, v72
	v_fmac_f32_e32 v73, v74, v71
	v_fma_f32 v70, -v70, v73, v72
	v_div_fmas_f32 v70, v70, v71, v73
	v_div_fixup_f32 v69, v70, v69, 1.0
	v_div_scale_f32 v70, s[2:3], v68, v68, 1.0
	v_rcp_f32_e32 v71, v70
	s_nop 0
	v_fma_f32 v72, -v70, v71, 1.0
	v_fmac_f32_e32 v71, v72, v71
	v_div_scale_f32 v72, vcc, 1.0, v68, 1.0
	v_mul_f32_e32 v73, v72, v71
	v_fma_f32 v74, -v70, v73, v72
	v_fmac_f32_e32 v73, v74, v71
	v_fma_f32 v70, -v70, v73, v72
	v_div_fmas_f32 v70, v70, v71, v73
	v_div_fixup_f32 v68, v70, v68, 1.0
	v_pk_fma_f32 v[140:141], v[38:39], v[68:69], v[140:141]
	s_waitcnt vmcnt(30)
	v_cvt_f32_f16_e32 v68, v214
	v_cvt_f32_f16_e32 v69, v215
	v_add_u32_e32 v96, 0x98400, v94
	global_load_ushort v214, v96, s[40:41] offset:64
	v_add_u32_e32 v96, 0x9be00, v94
	global_load_ushort v215, v96, s[40:41] offset:64
	v_mul_f32_e32 v68, 0xbfb8aa3b, v68
	v_mul_f32_e32 v69, 0xbfb8aa3b, v69
	v_exp_f32_e32 v68, v68
	v_exp_f32_e32 v69, v69
	s_nop 0
	v_pk_add_f32 v[68:69], v[68:69], 1.0 op_sel_hi:[1,0]
	s_nop 0
	v_div_scale_f32 v70, s[2:3], v69, v69, 1.0
	v_rcp_f32_e32 v71, v70
	s_nop 0
	v_fma_f32 v72, -v70, v71, 1.0
	v_fmac_f32_e32 v71, v72, v71
	v_div_scale_f32 v72, vcc, 1.0, v69, 1.0
	v_mul_f32_e32 v73, v72, v71
	v_fma_f32 v74, -v70, v73, v72
	v_fmac_f32_e32 v73, v74, v71
	v_fma_f32 v70, -v70, v73, v72
	v_div_fmas_f32 v70, v70, v71, v73
	v_div_fixup_f32 v69, v70, v69, 1.0
	v_div_scale_f32 v70, s[2:3], v68, v68, 1.0
	v_rcp_f32_e32 v71, v70
	s_nop 0
	v_fma_f32 v72, -v70, v71, 1.0
	v_fmac_f32_e32 v71, v72, v71
	v_div_scale_f32 v72, vcc, 1.0, v68, 1.0
	v_mul_f32_e32 v73, v72, v71
	v_fma_f32 v74, -v70, v73, v72
	v_fmac_f32_e32 v73, v74, v71
	v_fma_f32 v70, -v70, v73, v72
	v_div_fmas_f32 v70, v70, v71, v73
	v_div_fixup_f32 v68, v70, v68, 1.0
	v_pk_fma_f32 v[138:139], v[40:41], v[68:69], v[138:139]
	s_waitcnt vmcnt(30)
;   __device__ __forceinline__ const float* x() const { return (const float*)(const __attribute__((address_space(1))) float*)kp[0]; }
; __device__ __forceinline__ float sigmoidf_(float x) { return 1.f / (1.f + __expf(-x)); }
; __device__ __forceinline__ void phase_merge(const KP& p, char* smem, int* q, int xcc) {
;     ...
;           [&](int mi, int ni, int r, int row, int col, float v) {
;             const float gz = (float)G[(size_t)row * NU + col];
;             tot[mi][ni][r] += sigmoidf_(gz) * v;
;           },
	v_cvt_f32_f16_e32 v68, v216
	v_cvt_f32_f16_e32 v69, v217
	v_add_u32_e32 v96, 0xae000, v94
	global_load_ushort v216, v96, s[40:41] offset:64
	v_add_u32_e32 v96, 0xb1a00, v94
	global_load_ushort v217, v96, s[40:41] offset:64
	v_mul_f32_e32 v68, 0xbfb8aa3b, v68
	v_mul_f32_e32 v69, 0xbfb8aa3b, v69
	v_exp_f32_e32 v68, v68
	v_exp_f32_e32 v69, v69
	s_nop 0
	v_pk_add_f32 v[68:69], v[68:69], 1.0 op_sel_hi:[1,0]
	s_nop 0
	v_div_scale_f32 v70, s[2:3], v69, v69, 1.0
	v_rcp_f32_e32 v71, v70
	s_nop 0
	v_fma_f32 v72, -v70, v71, 1.0
	v_fmac_f32_e32 v71, v72, v71
	v_div_scale_f32 v72, vcc, 1.0, v69, 1.0
	v_mul_f32_e32 v73, v72, v71
	v_fma_f32 v74, -v70, v73, v72
	v_fmac_f32_e32 v73, v74, v71
	v_fma_f32 v70, -v70, v73, v72
	v_div_fmas_f32 v70, v70, v71, v73
	v_div_fixup_f32 v69, v70, v69, 1.0
	v_div_scale_f32 v70, s[2:3], v68, v68, 1.0
	v_rcp_f32_e32 v71, v70
	s_nop 0
	v_fma_f32 v72, -v70, v71, 1.0
	v_fmac_f32_e32 v71, v72, v71
	v_div_scale_f32 v72, vcc, 1.0, v68, 1.0
	v_mul_f32_e32 v73, v72, v71
	v_fma_f32 v74, -v70, v73, v72
	v_fmac_f32_e32 v73, v74, v71
	v_fma_f32 v70, -v70, v73, v72
	v_div_fmas_f32 v70, v70, v71, v73
	v_div_fixup_f32 v68, v70, v68, 1.0
	v_pk_fma_f32 v[136:137], v[42:43], v[68:69], v[136:137]
	s_waitcnt vmcnt(30)
	v_cvt_f32_f16_e32 v68, v218
	v_cvt_f32_f16_e32 v69, v219
	v_add_u32_e32 v96, 0xb5400, v94
	global_load_ushort v218, v96, s[40:41] offset:64
	v_add_u32_e32 v96, 0xb8e00, v94
	global_load_ushort v219, v96, s[40:41] offset:64
	v_mul_f32_e32 v68, 0xbfb8aa3b, v68
	v_mul_f32_e32 v69, 0xbfb8aa3b, v69
	v_exp_f32_e32 v68, v68
	v_exp_f32_e32 v69, v69
	s_nop 0
	v_pk_add_f32 v[68:69], v[68:69], 1.0 op_sel_hi:[1,0]
	s_nop 0
	v_div_scale_f32 v70, s[2:3], v69, v69, 1.0
	v_rcp_f32_e32 v71, v70
	s_nop 0
	v_fma_f32 v72, -v70, v71, 1.0
	v_fmac_f32_e32 v71, v72, v71
	v_div_scale_f32 v72, vcc, 1.0, v69, 1.0
	v_mul_f32_e32 v73, v72, v71
	v_fma_f32 v74, -v70, v73, v72
	v_fmac_f32_e32 v73, v74, v71
	v_fma_f32 v70, -v70, v73, v72
	v_div_fmas_f32 v70, v70, v71, v73
	v_div_fixup_f32 v69, v70, v69, 1.0
	v_div_scale_f32 v70, s[2:3], v68, v68, 1.0
	v_rcp_f32_e32 v71, v70
	s_nop 0
	v_fma_f32 v72, -v70, v71, 1.0
	v_fmac_f32_e32 v71, v72, v71
	v_div_scale_f32 v72, vcc, 1.0, v68, 1.0
	v_mul_f32_e32 v73, v72, v71
	v_fma_f32 v74, -v70, v73, v72
	v_fmac_f32_e32 v73, v74, v71
	v_fma_f32 v70, -v70, v73, v72
	v_div_fmas_f32 v70, v70, v71, v73
	v_div_fixup_f32 v68, v70, v68, 1.0
	v_pk_fma_f32 v[134:135], v[44:45], v[68:69], v[134:135]
	s_waitcnt vmcnt(30)
	v_cvt_f32_f16_e32 v68, v220
	v_cvt_f32_f16_e32 v69, v221
	v_add_u32_e32 v96, 0xcb000, v94
	global_load_ushort v220, v96, s[40:41] offset:64
	v_add_u32_e32 v96, 0xcea00, v94
	global_load_ushort v221, v96, s[40:41] offset:64
	v_mul_f32_e32 v68, 0xbfb8aa3b, v68
	v_mul_f32_e32 v69, 0xbfb8aa3b, v69
	v_exp_f32_e32 v68, v68
	v_exp_f32_e32 v69, v69
	s_nop 0
	v_pk_add_f32 v[68:69], v[68:69], 1.0 op_sel_hi:[1,0]
	s_nop 0
	v_div_scale_f32 v70, s[2:3], v69, v69, 1.0
	v_rcp_f32_e32 v71, v70
	s_nop 0
	v_fma_f32 v72, -v70, v71, 1.0
	v_fmac_f32_e32 v71, v72, v71
	v_div_scale_f32 v72, vcc, 1.0, v69, 1.0
	v_mul_f32_e32 v73, v72, v71
	v_fma_f32 v74, -v70, v73, v72
	v_fmac_f32_e32 v73, v74, v71
	v_fma_f32 v70, -v70, v73, v72
	v_div_fmas_f32 v70, v70, v71, v73
	v_div_fixup_f32 v69, v70, v69, 1.0
	v_div_scale_f32 v70, s[2:3], v68, v68, 1.0
	v_rcp_f32_e32 v71, v70
	s_nop 0
	v_fma_f32 v72, -v70, v71, 1.0
	v_fmac_f32_e32 v71, v72, v71
	v_div_scale_f32 v72, vcc, 1.0, v68, 1.0
	v_mul_f32_e32 v73, v72, v71
	v_fma_f32 v74, -v70, v73, v72
	v_fmac_f32_e32 v73, v74, v71
	v_fma_f32 v70, -v70, v73, v72
	v_div_fmas_f32 v70, v70, v71, v73
	v_div_fixup_f32 v68, v70, v68, 1.0
	v_pk_fma_f32 v[132:133], v[46:47], v[68:69], v[132:133]
	s_waitcnt vmcnt(30)
	v_cvt_f32_f16_e32 v68, v222
	v_cvt_f32_f16_e32 v69, v223
	v_add_u32_e32 v96, 0xd2400, v94
	global_load_ushort v222, v96, s[40:41] offset:64
	v_add_u32_e32 v96, 0xd5e00, v94
	global_load_ushort v223, v96, s[40:41] offset:64
	v_mul_f32_e32 v68, 0xbfb8aa3b, v68
	v_mul_f32_e32 v69, 0xbfb8aa3b, v69
	v_exp_f32_e32 v68, v68
	v_exp_f32_e32 v69, v69
	s_nop 0
	v_pk_add_f32 v[68:69], v[68:69], 1.0 op_sel_hi:[1,0]
	s_nop 0
	v_div_scale_f32 v70, s[2:3], v69, v69, 1.0
	v_rcp_f32_e32 v71, v70
	s_nop 0
	v_fma_f32 v72, -v70, v71, 1.0
	v_fmac_f32_e32 v71, v72, v71
	v_div_scale_f32 v72, vcc, 1.0, v69, 1.0
	v_mul_f32_e32 v73, v72, v71
	v_fma_f32 v74, -v70, v73, v72
	v_fmac_f32_e32 v73, v74, v71
	v_fma_f32 v70, -v70, v73, v72
	v_div_fmas_f32 v70, v70, v71, v73
	v_div_fixup_f32 v69, v70, v69, 1.0
	v_div_scale_f32 v70, s[2:3], v68, v68, 1.0
	v_rcp_f32_e32 v71, v70
	s_nop 0
	v_fma_f32 v72, -v70, v71, 1.0
	v_fmac_f32_e32 v71, v72, v71
	v_div_scale_f32 v72, vcc, 1.0, v68, 1.0
	v_mul_f32_e32 v73, v72, v71
	v_fma_f32 v74, -v70, v73, v72
	v_fmac_f32_e32 v73, v74, v71
	v_fma_f32 v70, -v70, v73, v72
	v_div_fmas_f32 v70, v70, v71, v73
	v_div_fixup_f32 v68, v70, v68, 1.0
	v_pk_fma_f32 v[130:131], v[48:49], v[68:69], v[130:131]
	s_waitcnt vmcnt(30)
	v_cvt_f32_f16_e32 v68, v192
	v_cvt_f32_f16_e32 v69, v193
	v_mul_f32_e32 v68, 0xbfb8aa3b, v68
	v_mul_f32_e32 v69, 0xbfb8aa3b, v69
	v_exp_f32_e32 v68, v68
	v_exp_f32_e32 v69, v69
	s_nop 0
	v_pk_add_f32 v[68:69], v[68:69], 1.0 op_sel_hi:[1,0]
	s_nop 0
	v_div_scale_f32 v70, s[2:3], v69, v69, 1.0
	v_rcp_f32_e32 v71, v70
	s_nop 0
	v_fma_f32 v72, -v70, v71, 1.0
	v_fmac_f32_e32 v71, v72, v71
	v_div_scale_f32 v72, vcc, 1.0, v69, 1.0
	v_mul_f32_e32 v73, v72, v71
	v_fma_f32 v74, -v70, v73, v72
	v_fmac_f32_e32 v73, v74, v71
	v_fma_f32 v70, -v70, v73, v72
	v_div_fmas_f32 v70, v70, v71, v73
	v_div_fixup_f32 v69, v70, v69, 1.0
	v_div_scale_f32 v70, s[2:3], v68, v68, 1.0
	v_rcp_f32_e32 v71, v70
	s_nop 0
	v_fma_f32 v72, -v70, v71, 1.0
	v_fmac_f32_e32 v71, v72, v71
	v_div_scale_f32 v72, vcc, 1.0, v68, 1.0
	v_mul_f32_e32 v73, v72, v71
	v_fma_f32 v74, -v70, v73, v72
	v_fmac_f32_e32 v73, v74, v71
	v_fma_f32 v70, -v70, v73, v72
	v_div_fmas_f32 v70, v70, v71, v73
	v_div_fixup_f32 v68, v70, v68, 1.0
	v_pk_fma_f32 v[128:129], v[18:19], v[68:69], v[128:129]
	s_waitcnt vmcnt(28)
;   __device__ __forceinline__ const float* x() const { return (const float*)(const __attribute__((address_space(1))) float*)kp[0]; }
; __device__ __forceinline__ float sigmoidf_(float x) { return 1.f / (1.f + __expf(-x)); }
; __device__ __forceinline__ void phase_merge(const KP& p, char* smem, int* q, int xcc) {
;     ...
;           [&](int mi, int ni, int r, int row, int col, float v) {
;             const float gz = (float)G[(size_t)row * NU + col];
;             tot[mi][ni][r] += sigmoidf_(gz) * v;
;           },
	v_cvt_f32_f16_e32 v68, v194
	v_cvt_f32_f16_e32 v69, v195
	v_mul_f32_e32 v68, 0xbfb8aa3b, v68
	v_mul_f32_e32 v69, 0xbfb8aa3b, v69
	v_exp_f32_e32 v68, v68
	v_exp_f32_e32 v69, v69
	s_nop 0
	v_pk_add_f32 v[68:69], v[68:69], 1.0 op_sel_hi:[1,0]
	s_nop 0
	v_div_scale_f32 v70, s[2:3], v69, v69, 1.0
	v_rcp_f32_e32 v71, v70
	s_nop 0
	v_fma_f32 v72, -v70, v71, 1.0
	v_fmac_f32_e32 v71, v72, v71
	v_div_scale_f32 v72, vcc, 1.0, v69, 1.0
	v_mul_f32_e32 v73, v72, v71
	v_fma_f32 v74, -v70, v73, v72
	v_fmac_f32_e32 v73, v74, v71
	v_fma_f32 v70, -v70, v73, v72
	v_div_fmas_f32 v70, v70, v71, v73
	v_div_fixup_f32 v69, v70, v69, 1.0
	v_div_scale_f32 v70, s[2:3], v68, v68, 1.0
	v_rcp_f32_e32 v71, v70
	s_nop 0
	v_fma_f32 v72, -v70, v71, 1.0
	v_fmac_f32_e32 v71, v72, v71
	v_div_scale_f32 v72, vcc, 1.0, v68, 1.0
	v_mul_f32_e32 v73, v72, v71
	v_fma_f32 v74, -v70, v73, v72
	v_fmac_f32_e32 v73, v74, v71
	v_fma_f32 v70, -v70, v73, v72
	v_div_fmas_f32 v70, v70, v71, v73
	v_div_fixup_f32 v68, v70, v68, 1.0
	v_pk_fma_f32 v[126:127], v[20:21], v[68:69], v[126:127]
	s_waitcnt vmcnt(26)
	v_cvt_f32_f16_e32 v68, v196
	v_cvt_f32_f16_e32 v69, v197
	v_mul_f32_e32 v68, 0xbfb8aa3b, v68
	v_mul_f32_e32 v69, 0xbfb8aa3b, v69
	v_exp_f32_e32 v68, v68
	v_exp_f32_e32 v69, v69
	s_nop 0
	v_pk_add_f32 v[68:69], v[68:69], 1.0 op_sel_hi:[1,0]
	s_nop 0
	v_div_scale_f32 v70, s[2:3], v69, v69, 1.0
	v_rcp_f32_e32 v71, v70
	s_nop 0
	v_fma_f32 v72, -v70, v71, 1.0
	v_fmac_f32_e32 v71, v72, v71
	v_div_scale_f32 v72, vcc, 1.0, v69, 1.0
	v_mul_f32_e32 v73, v72, v71
	v_fma_f32 v74, -v70, v73, v72
	v_fmac_f32_e32 v73, v74, v71
	v_fma_f32 v70, -v70, v73, v72
	v_div_fmas_f32 v70, v70, v71, v73
	v_div_fixup_f32 v69, v70, v69, 1.0
	v_div_scale_f32 v70, s[2:3], v68, v68, 1.0
	v_rcp_f32_e32 v71, v70
	s_nop 0
	v_fma_f32 v72, -v70, v71, 1.0
	v_fmac_f32_e32 v71, v72, v71
	v_div_scale_f32 v72, vcc, 1.0, v68, 1.0
	v_mul_f32_e32 v73, v72, v71
	v_fma_f32 v74, -v70, v73, v72
	v_fmac_f32_e32 v73, v74, v71
	v_fma_f32 v70, -v70, v73, v72
	v_div_fmas_f32 v70, v70, v71, v73
	v_div_fixup_f32 v68, v70, v68, 1.0
	v_pk_fma_f32 v[124:125], v[22:23], v[68:69], v[124:125]
	s_waitcnt vmcnt(24)
	v_cvt_f32_f16_e32 v68, v198
	v_cvt_f32_f16_e32 v69, v199
	v_mul_f32_e32 v68, 0xbfb8aa3b, v68
	v_mul_f32_e32 v69, 0xbfb8aa3b, v69
	v_exp_f32_e32 v68, v68
	v_exp_f32_e32 v69, v69
	s_nop 0
	v_pk_add_f32 v[68:69], v[68:69], 1.0 op_sel_hi:[1,0]
	s_nop 0
	v_div_scale_f32 v70, s[2:3], v69, v69, 1.0
	v_rcp_f32_e32 v71, v70
	s_nop 0
	v_fma_f32 v72, -v70, v71, 1.0
	v_fmac_f32_e32 v71, v72, v71
	v_div_scale_f32 v72, vcc, 1.0, v69, 1.0
	v_mul_f32_e32 v73, v72, v71
	v_fma_f32 v74, -v70, v73, v72
	v_fmac_f32_e32 v73, v74, v71
	v_fma_f32 v70, -v70, v73, v72
	v_div_fmas_f32 v70, v70, v71, v73
	v_div_fixup_f32 v69, v70, v69, 1.0
	v_div_scale_f32 v70, s[2:3], v68, v68, 1.0
	v_rcp_f32_e32 v71, v70
	s_nop 0
	v_fma_f32 v72, -v70, v71, 1.0
	v_fmac_f32_e32 v71, v72, v71
	v_div_scale_f32 v72, vcc, 1.0, v68, 1.0
	v_mul_f32_e32 v73, v72, v71
	v_fma_f32 v74, -v70, v73, v72
	v_fmac_f32_e32 v73, v74, v71
	v_fma_f32 v70, -v70, v73, v72
	v_div_fmas_f32 v70, v70, v71, v73
	v_div_fixup_f32 v68, v70, v68, 1.0
	v_pk_fma_f32 v[122:123], v[24:25], v[68:69], v[122:123]
	s_waitcnt vmcnt(22)
	v_cvt_f32_f16_e32 v68, v200
	v_cvt_f32_f16_e32 v69, v201
	v_mul_f32_e32 v68, 0xbfb8aa3b, v68
	v_mul_f32_e32 v69, 0xbfb8aa3b, v69
	v_exp_f32_e32 v68, v68
	v_exp_f32_e32 v69, v69
	s_nop 0
	v_pk_add_f32 v[68:69], v[68:69], 1.0 op_sel_hi:[1,0]
	s_nop 0
	v_div_scale_f32 v70, s[2:3], v69, v69, 1.0
	v_rcp_f32_e32 v71, v70
	s_nop 0
	v_fma_f32 v72, -v70, v71, 1.0
	v_fmac_f32_e32 v71, v72, v71
	v_div_scale_f32 v72, vcc, 1.0, v69, 1.0
	v_mul_f32_e32 v73, v72, v71
	v_fma_f32 v74, -v70, v73, v72
	v_fmac_f32_e32 v73, v74, v71
	v_fma_f32 v70, -v70, v73, v72
	v_div_fmas_f32 v70, v70, v71, v73
	v_div_fixup_f32 v69, v70, v69, 1.0
	v_div_scale_f32 v70, s[2:3], v68, v68, 1.0
	v_rcp_f32_e32 v71, v70
	s_nop 0
	v_fma_f32 v72, -v70, v71, 1.0
	v_fmac_f32_e32 v71, v72, v71
	v_div_scale_f32 v72, vcc, 1.0, v68, 1.0
	v_mul_f32_e32 v73, v72, v71
	v_fma_f32 v74, -v70, v73, v72
	v_fmac_f32_e32 v73, v74, v71
	v_fma_f32 v70, -v70, v73, v72
	v_div_fmas_f32 v70, v70, v71, v73
	v_div_fixup_f32 v68, v70, v68, 1.0
	v_pk_fma_f32 v[120:121], v[26:27], v[68:69], v[120:121]
	s_waitcnt vmcnt(20)
	v_cvt_f32_f16_e32 v68, v202
	v_cvt_f32_f16_e32 v69, v203
	v_mul_f32_e32 v68, 0xbfb8aa3b, v68
	v_mul_f32_e32 v69, 0xbfb8aa3b, v69
	v_exp_f32_e32 v68, v68
	v_exp_f32_e32 v69, v69
	s_nop 0
	v_pk_add_f32 v[68:69], v[68:69], 1.0 op_sel_hi:[1,0]
	s_nop 0
	v_div_scale_f32 v70, s[2:3], v69, v69, 1.0
	v_rcp_f32_e32 v71, v70
	s_nop 0
	v_fma_f32 v72, -v70, v71, 1.0
	v_fmac_f32_e32 v71, v72, v71
	v_div_scale_f32 v72, vcc, 1.0, v69, 1.0
	v_mul_f32_e32 v73, v72, v71
	v_fma_f32 v74, -v70, v73, v72
	v_fmac_f32_e32 v73, v74, v71
	v_fma_f32 v70, -v70, v73, v72
	v_div_fmas_f32 v70, v70, v71, v73
	v_div_fixup_f32 v69, v70, v69, 1.0
	v_div_scale_f32 v70, s[2:3], v68, v68, 1.0
	v_rcp_f32_e32 v71, v70
	s_nop 0
	v_fma_f32 v72, -v70, v71, 1.0
	v_fmac_f32_e32 v71, v72, v71
	v_div_scale_f32 v72, vcc, 1.0, v68, 1.0
	v_mul_f32_e32 v73, v72, v71
	v_fma_f32 v74, -v70, v73, v72
	v_fmac_f32_e32 v73, v74, v71
	v_fma_f32 v70, -v70, v73, v72
	v_div_fmas_f32 v70, v70, v71, v73
	v_div_fixup_f32 v68, v70, v68, 1.0
	v_pk_fma_f32 v[118:119], v[28:29], v[68:69], v[118:119]
	s_waitcnt vmcnt(18)
;   __device__ __forceinline__ const float* x() const { return (const float*)(const __attribute__((address_space(1))) float*)kp[0]; }
; __device__ __forceinline__ float sigmoidf_(float x) { return 1.f / (1.f + __expf(-x)); }
; __device__ __forceinline__ void phase_merge(const KP& p, char* smem, int* q, int xcc) {
;     ...
;           [&](int mi, int ni, int r, int row, int col, float v) {
;             const float gz = (float)G[(size_t)row * NU + col];
;             tot[mi][ni][r] += sigmoidf_(gz) * v;
;           },
	v_cvt_f32_f16_e32 v68, v204
	v_cvt_f32_f16_e32 v69, v205
	v_mul_f32_e32 v68, 0xbfb8aa3b, v68
	v_mul_f32_e32 v69, 0xbfb8aa3b, v69
	v_exp_f32_e32 v68, v68
	v_exp_f32_e32 v69, v69
	s_nop 0
	v_pk_add_f32 v[68:69], v[68:69], 1.0 op_sel_hi:[1,0]
	s_nop 0
	v_div_scale_f32 v70, s[2:3], v69, v69, 1.0
	v_rcp_f32_e32 v71, v70
	s_nop 0
	v_fma_f32 v72, -v70, v71, 1.0
	v_fmac_f32_e32 v71, v72, v71
	v_div_scale_f32 v72, vcc, 1.0, v69, 1.0
	v_mul_f32_e32 v73, v72, v71
	v_fma_f32 v74, -v70, v73, v72
	v_fmac_f32_e32 v73, v74, v71
	v_fma_f32 v70, -v70, v73, v72
	v_div_fmas_f32 v70, v70, v71, v73
	v_div_fixup_f32 v69, v70, v69, 1.0
	v_div_scale_f32 v70, s[2:3], v68, v68, 1.0
	v_rcp_f32_e32 v71, v70
	s_nop 0
	v_fma_f32 v72, -v70, v71, 1.0
	v_fmac_f32_e32 v71, v72, v71
	v_div_scale_f32 v72, vcc, 1.0, v68, 1.0
	v_mul_f32_e32 v73, v72, v71
	v_fma_f32 v74, -v70, v73, v72
	v_fmac_f32_e32 v73, v74, v71
	v_fma_f32 v70, -v70, v73, v72
	v_div_fmas_f32 v70, v70, v71, v73
	v_div_fixup_f32 v68, v70, v68, 1.0
	v_pk_fma_f32 v[116:117], v[30:31], v[68:69], v[116:117]
	s_waitcnt vmcnt(16)
	v_cvt_f32_f16_e32 v68, v206
	v_cvt_f32_f16_e32 v69, v207
	v_mul_f32_e32 v68, 0xbfb8aa3b, v68
	v_mul_f32_e32 v69, 0xbfb8aa3b, v69
	v_exp_f32_e32 v68, v68
	v_exp_f32_e32 v69, v69
	s_nop 0
	v_pk_add_f32 v[68:69], v[68:69], 1.0 op_sel_hi:[1,0]
	s_nop 0
	v_div_scale_f32 v70, s[2:3], v69, v69, 1.0
	v_rcp_f32_e32 v71, v70
	s_nop 0
	v_fma_f32 v72, -v70, v71, 1.0
	v_fmac_f32_e32 v71, v72, v71
	v_div_scale_f32 v72, vcc, 1.0, v69, 1.0
	v_mul_f32_e32 v73, v72, v71
	v_fma_f32 v74, -v70, v73, v72
	v_fmac_f32_e32 v73, v74, v71
	v_fma_f32 v70, -v70, v73, v72
	v_div_fmas_f32 v70, v70, v71, v73
	v_div_fixup_f32 v69, v70, v69, 1.0
	v_div_scale_f32 v70, s[2:3], v68, v68, 1.0
	v_rcp_f32_e32 v71, v70
	s_nop 0
	v_fma_f32 v72, -v70, v71, 1.0
	v_fmac_f32_e32 v71, v72, v71
	v_div_scale_f32 v72, vcc, 1.0, v68, 1.0
	v_mul_f32_e32 v73, v72, v71
	v_fma_f32 v74, -v70, v73, v72
	v_fmac_f32_e32 v73, v74, v71
	v_fma_f32 v70, -v70, v73, v72
	v_div_fmas_f32 v70, v70, v71, v73
	v_div_fixup_f32 v68, v70, v68, 1.0
	v_pk_fma_f32 v[114:115], v[32:33], v[68:69], v[114:115]
	s_waitcnt vmcnt(14)
	v_cvt_f32_f16_e32 v68, v208
	v_cvt_f32_f16_e32 v69, v209
	v_mul_f32_e32 v68, 0xbfb8aa3b, v68
	v_mul_f32_e32 v69, 0xbfb8aa3b, v69
	v_exp_f32_e32 v68, v68
	v_exp_f32_e32 v69, v69
	s_nop 0
	v_pk_add_f32 v[68:69], v[68:69], 1.0 op_sel_hi:[1,0]
	s_nop 0
	v_div_scale_f32 v70, s[2:3], v69, v69, 1.0
	v_rcp_f32_e32 v71, v70
	s_nop 0
	v_fma_f32 v72, -v70, v71, 1.0
	v_fmac_f32_e32 v71, v72, v71
	v_div_scale_f32 v72, vcc, 1.0, v69, 1.0
	v_mul_f32_e32 v73, v72, v71
	v_fma_f32 v74, -v70, v73, v72
	v_fmac_f32_e32 v73, v74, v71
	v_fma_f32 v70, -v70, v73, v72
	v_div_fmas_f32 v70, v70, v71, v73
	v_div_fixup_f32 v69, v70, v69, 1.0
	v_div_scale_f32 v70, s[2:3], v68, v68, 1.0
	v_rcp_f32_e32 v71, v70
	s_nop 0
	v_fma_f32 v72, -v70, v71, 1.0
	v_fmac_f32_e32 v71, v72, v71
	v_div_scale_f32 v72, vcc, 1.0, v68, 1.0
	v_mul_f32_e32 v73, v72, v71
	v_fma_f32 v74, -v70, v73, v72
	v_fmac_f32_e32 v73, v74, v71
	v_fma_f32 v70, -v70, v73, v72
	v_div_fmas_f32 v70, v70, v71, v73
	v_div_fixup_f32 v68, v70, v68, 1.0
	v_pk_fma_f32 v[112:113], v[2:3], v[68:69], v[112:113]
	s_waitcnt vmcnt(12)
	v_cvt_f32_f16_e32 v68, v210
	v_cvt_f32_f16_e32 v69, v211
	v_mul_f32_e32 v68, 0xbfb8aa3b, v68
	v_mul_f32_e32 v69, 0xbfb8aa3b, v69
	v_exp_f32_e32 v68, v68
	v_exp_f32_e32 v69, v69
	s_nop 0
	v_pk_add_f32 v[68:69], v[68:69], 1.0 op_sel_hi:[1,0]
	s_nop 0
	v_div_scale_f32 v70, s[2:3], v69, v69, 1.0
	v_rcp_f32_e32 v71, v70
	s_nop 0
	v_fma_f32 v72, -v70, v71, 1.0
	v_fmac_f32_e32 v71, v72, v71
	v_div_scale_f32 v72, vcc, 1.0, v69, 1.0
	v_mul_f32_e32 v73, v72, v71
	v_fma_f32 v74, -v70, v73, v72
	v_fmac_f32_e32 v73, v74, v71
	v_fma_f32 v70, -v70, v73, v72
	v_div_fmas_f32 v70, v70, v71, v73
	v_div_fixup_f32 v69, v70, v69, 1.0
	v_div_scale_f32 v70, s[2:3], v68, v68, 1.0
	v_rcp_f32_e32 v71, v70
	s_nop 0
	v_fma_f32 v72, -v70, v71, 1.0
	v_fmac_f32_e32 v71, v72, v71
	v_div_scale_f32 v72, vcc, 1.0, v68, 1.0
	v_mul_f32_e32 v73, v72, v71
	v_fma_f32 v74, -v70, v73, v72
	v_fmac_f32_e32 v73, v74, v71
	v_fma_f32 v70, -v70, v73, v72
	v_div_fmas_f32 v70, v70, v71, v73
	v_div_fixup_f32 v68, v70, v68, 1.0
	v_pk_fma_f32 v[110:111], v[4:5], v[68:69], v[110:111]
	s_waitcnt vmcnt(10)
	v_cvt_f32_f16_e32 v68, v212
	v_cvt_f32_f16_e32 v69, v213
	v_mul_f32_e32 v68, 0xbfb8aa3b, v68
	v_mul_f32_e32 v69, 0xbfb8aa3b, v69
	v_exp_f32_e32 v68, v68
	v_exp_f32_e32 v69, v69
	s_nop 0
	v_pk_add_f32 v[68:69], v[68:69], 1.0 op_sel_hi:[1,0]
	s_nop 0
	v_div_scale_f32 v70, s[2:3], v69, v69, 1.0
	v_rcp_f32_e32 v71, v70
	s_nop 0
	v_fma_f32 v72, -v70, v71, 1.0
	v_fmac_f32_e32 v71, v72, v71
	v_div_scale_f32 v72, vcc, 1.0, v69, 1.0
	v_mul_f32_e32 v73, v72, v71
	v_fma_f32 v74, -v70, v73, v72
	v_fmac_f32_e32 v73, v74, v71
	v_fma_f32 v70, -v70, v73, v72
	v_div_fmas_f32 v70, v70, v71, v73
	v_div_fixup_f32 v69, v70, v69, 1.0
	v_div_scale_f32 v70, s[2:3], v68, v68, 1.0
	v_rcp_f32_e32 v71, v70
	s_nop 0
	v_fma_f32 v72, -v70, v71, 1.0
	v_fmac_f32_e32 v71, v72, v71
	v_div_scale_f32 v72, vcc, 1.0, v68, 1.0
	v_mul_f32_e32 v73, v72, v71
	v_fma_f32 v74, -v70, v73, v72
	v_fmac_f32_e32 v73, v74, v71
	v_fma_f32 v70, -v70, v73, v72
	v_div_fmas_f32 v70, v70, v71, v73
	v_div_fixup_f32 v68, v70, v68, 1.0
	v_pk_fma_f32 v[108:109], v[6:7], v[68:69], v[108:109]
	s_waitcnt vmcnt(8)
;   __device__ __forceinline__ const float* x() const { return (const float*)(const __attribute__((address_space(1))) float*)kp[0]; }
; __device__ __forceinline__ float sigmoidf_(float x) { return 1.f / (1.f + __expf(-x)); }
; __device__ __forceinline__ void phase_merge(const KP& p, char* smem, int* q, int xcc) {
;     ...
;           [&](int mi, int ni, int r, int row, int col, float v) {
;             const float gz = (float)G[(size_t)row * NU + col];
;             tot[mi][ni][r] += sigmoidf_(gz) * v;
;           },
	v_cvt_f32_f16_e32 v68, v214
	v_cvt_f32_f16_e32 v69, v215
	v_mul_f32_e32 v68, 0xbfb8aa3b, v68
	v_mul_f32_e32 v69, 0xbfb8aa3b, v69
	v_exp_f32_e32 v68, v68
	v_exp_f32_e32 v69, v69
	s_nop 0
	v_pk_add_f32 v[68:69], v[68:69], 1.0 op_sel_hi:[1,0]
	s_nop 0
	v_div_scale_f32 v70, s[2:3], v69, v69, 1.0
	v_rcp_f32_e32 v71, v70
	s_nop 0
	v_fma_f32 v72, -v70, v71, 1.0
	v_fmac_f32_e32 v71, v72, v71
	v_div_scale_f32 v72, vcc, 1.0, v69, 1.0
	v_mul_f32_e32 v73, v72, v71
	v_fma_f32 v74, -v70, v73, v72
	v_fmac_f32_e32 v73, v74, v71
	v_fma_f32 v70, -v70, v73, v72
	v_div_fmas_f32 v70, v70, v71, v73
	v_div_fixup_f32 v69, v70, v69, 1.0
	v_div_scale_f32 v70, s[2:3], v68, v68, 1.0
	v_rcp_f32_e32 v71, v70
	s_nop 0
	v_fma_f32 v72, -v70, v71, 1.0
	v_fmac_f32_e32 v71, v72, v71
	v_div_scale_f32 v72, vcc, 1.0, v68, 1.0
	v_mul_f32_e32 v73, v72, v71
	v_fma_f32 v74, -v70, v73, v72
	v_fmac_f32_e32 v73, v74, v71
	v_fma_f32 v70, -v70, v73, v72
	v_div_fmas_f32 v70, v70, v71, v73
	v_div_fixup_f32 v68, v70, v68, 1.0
	v_pk_fma_f32 v[106:107], v[8:9], v[68:69], v[106:107]
	s_waitcnt vmcnt(6)
	v_cvt_f32_f16_e32 v68, v216
	v_cvt_f32_f16_e32 v69, v217
	v_mul_f32_e32 v68, 0xbfb8aa3b, v68
	v_mul_f32_e32 v69, 0xbfb8aa3b, v69
	v_exp_f32_e32 v68, v68
	v_exp_f32_e32 v69, v69
	s_nop 0
	v_pk_add_f32 v[68:69], v[68:69], 1.0 op_sel_hi:[1,0]
	s_nop 0
	v_div_scale_f32 v70, s[2:3], v69, v69, 1.0
	v_rcp_f32_e32 v71, v70
	s_nop 0
	v_fma_f32 v72, -v70, v71, 1.0
	v_fmac_f32_e32 v71, v72, v71
	v_div_scale_f32 v72, vcc, 1.0, v69, 1.0
	v_mul_f32_e32 v73, v72, v71
	v_fma_f32 v74, -v70, v73, v72
	v_fmac_f32_e32 v73, v74, v71
	v_fma_f32 v70, -v70, v73, v72
	v_div_fmas_f32 v70, v70, v71, v73
	v_div_fixup_f32 v69, v70, v69, 1.0
	v_div_scale_f32 v70, s[2:3], v68, v68, 1.0
	v_rcp_f32_e32 v71, v70
	s_nop 0
	v_fma_f32 v72, -v70, v71, 1.0
	v_fmac_f32_e32 v71, v72, v71
	v_div_scale_f32 v72, vcc, 1.0, v68, 1.0
	v_mul_f32_e32 v73, v72, v71
	v_fma_f32 v74, -v70, v73, v72
	v_fmac_f32_e32 v73, v74, v71
	v_fma_f32 v70, -v70, v73, v72
	v_div_fmas_f32 v70, v70, v71, v73
	v_div_fixup_f32 v68, v70, v68, 1.0
	v_pk_fma_f32 v[104:105], v[10:11], v[68:69], v[104:105]
	s_waitcnt vmcnt(4)
	v_cvt_f32_f16_e32 v68, v218
	v_cvt_f32_f16_e32 v69, v219
	v_mul_f32_e32 v68, 0xbfb8aa3b, v68
	v_mul_f32_e32 v69, 0xbfb8aa3b, v69
	v_exp_f32_e32 v68, v68
	v_exp_f32_e32 v69, v69
	s_nop 0
	v_pk_add_f32 v[68:69], v[68:69], 1.0 op_sel_hi:[1,0]
	s_nop 0
	v_div_scale_f32 v70, s[2:3], v69, v69, 1.0
	v_rcp_f32_e32 v71, v70
	s_nop 0
	v_fma_f32 v72, -v70, v71, 1.0
	v_fmac_f32_e32 v71, v72, v71
	v_div_scale_f32 v72, vcc, 1.0, v69, 1.0
	v_mul_f32_e32 v73, v72, v71
	v_fma_f32 v74, -v70, v73, v72
	v_fmac_f32_e32 v73, v74, v71
	v_fma_f32 v70, -v70, v73, v72
	v_div_fmas_f32 v70, v70, v71, v73
	v_div_fixup_f32 v69, v70, v69, 1.0
	v_div_scale_f32 v70, s[2:3], v68, v68, 1.0
	v_rcp_f32_e32 v71, v70
	s_nop 0
	v_fma_f32 v72, -v70, v71, 1.0
	v_fmac_f32_e32 v71, v72, v71
	v_div_scale_f32 v72, vcc, 1.0, v68, 1.0
	v_mul_f32_e32 v73, v72, v71
	v_fma_f32 v74, -v70, v73, v72
	v_fmac_f32_e32 v73, v74, v71
	v_fma_f32 v70, -v70, v73, v72
	v_div_fmas_f32 v70, v70, v71, v73
	v_div_fixup_f32 v68, v70, v68, 1.0
	v_pk_fma_f32 v[102:103], v[12:13], v[68:69], v[102:103]
	s_waitcnt vmcnt(2)
	v_cvt_f32_f16_e32 v68, v220
	v_cvt_f32_f16_e32 v69, v221
	v_mul_f32_e32 v68, 0xbfb8aa3b, v68
	v_mul_f32_e32 v69, 0xbfb8aa3b, v69
	v_exp_f32_e32 v68, v68
	v_exp_f32_e32 v69, v69
	s_nop 0
	v_pk_add_f32 v[68:69], v[68:69], 1.0 op_sel_hi:[1,0]
	s_nop 0
	v_div_scale_f32 v70, s[2:3], v69, v69, 1.0
	v_rcp_f32_e32 v71, v70
	s_nop 0
	v_fma_f32 v72, -v70, v71, 1.0
	v_fmac_f32_e32 v71, v72, v71
	v_div_scale_f32 v72, vcc, 1.0, v69, 1.0
	v_mul_f32_e32 v73, v72, v71
	v_fma_f32 v74, -v70, v73, v72
	v_fmac_f32_e32 v73, v74, v71
	v_fma_f32 v70, -v70, v73, v72
	v_div_fmas_f32 v70, v70, v71, v73
	v_div_fixup_f32 v69, v70, v69, 1.0
	v_div_scale_f32 v70, s[2:3], v68, v68, 1.0
	v_rcp_f32_e32 v71, v70
	s_nop 0
	v_fma_f32 v72, -v70, v71, 1.0
	v_fmac_f32_e32 v71, v72, v71
	v_div_scale_f32 v72, vcc, 1.0, v68, 1.0
	v_mul_f32_e32 v73, v72, v71
	v_fma_f32 v74, -v70, v73, v72
	v_fmac_f32_e32 v73, v74, v71
	v_fma_f32 v70, -v70, v73, v72
	v_div_fmas_f32 v70, v70, v71, v73
	v_div_fixup_f32 v68, v70, v68, 1.0
	v_pk_fma_f32 v[100:101], v[14:15], v[68:69], v[100:101]
	s_waitcnt vmcnt(0)
	v_cvt_f32_f16_e32 v68, v222
	v_cvt_f32_f16_e32 v69, v223
	v_mul_f32_e32 v68, 0xbfb8aa3b, v68
	v_mul_f32_e32 v69, 0xbfb8aa3b, v69
	v_exp_f32_e32 v68, v68
	v_exp_f32_e32 v69, v69
	s_nop 0
	v_pk_add_f32 v[68:69], v[68:69], 1.0 op_sel_hi:[1,0]
	s_nop 0
	v_div_scale_f32 v70, s[2:3], v69, v69, 1.0
	v_rcp_f32_e32 v71, v70
	s_nop 0
	v_fma_f32 v72, -v70, v71, 1.0
	v_fmac_f32_e32 v71, v72, v71
	v_div_scale_f32 v72, vcc, 1.0, v69, 1.0
	v_mul_f32_e32 v73, v72, v71
	v_fma_f32 v74, -v70, v73, v72
	v_fmac_f32_e32 v73, v74, v71
	v_fma_f32 v70, -v70, v73, v72
	v_div_fmas_f32 v70, v70, v71, v73
	v_div_fixup_f32 v69, v70, v69, 1.0
	v_div_scale_f32 v70, s[2:3], v68, v68, 1.0
	v_rcp_f32_e32 v71, v70
	s_nop 0
	v_fma_f32 v72, -v70, v71, 1.0
	v_fmac_f32_e32 v71, v72, v71
	v_div_scale_f32 v72, vcc, 1.0, v68, 1.0
	v_mul_f32_e32 v73, v72, v71
	v_fma_f32 v74, -v70, v73, v72
	v_fmac_f32_e32 v73, v74, v71
	v_fma_f32 v70, -v70, v73, v72
	v_div_fmas_f32 v70, v70, v71, v73
	v_div_fixup_f32 v68, v70, v68, 1.0
	v_pk_fma_f32 v[98:99], v[16:17], v[68:69], v[98:99]
	s_cmp_lg_u32 s56, 3
	s_cbranch_scc1 .LBB0_1742
;   __device__ __forceinline__ const float* x() const { return (const float*)(const __attribute__((address_space(1))) float*)kp[0]; }
;   __device__ __forceinline__ half_t* mm() const { return (half_t*)(ws() + OFF_mm); }
; __device__ __forceinline__ void phase_merge(const KP& p, char* smem, int* q, int xcc) {
;     ...
;     int tidx = threadIdx.x;
;     asm volatile("" : "+v"(tidx));
;     const int lane = tidx & 63, wid = tidx >> 6, wm = wid >> 1, wn = wid & 1;
; #pragma unroll
;     for (int mi = 0; mi < 2; ++mi)
; #pragma unroll
;       for (int ni = 0; ni < 2; ++ni)
; #pragma unroll
;         for (int r = 0; r < 16; ++r) {
;           const int row = wm * 64 + mi * 32 + (r & 3) + 8 * (r >> 2) + 4 * (lane >> 5);
;           const int col = wn * 64 + ni * 32 + (lane & 31);
;           p.mm()[(size_t)(m0 + row) * DM + n0 + col] = (half_t)tot[mi][ni][r];
;         }
	v_mov_b32_e32 v0, v224
	s_add_u32 s2, s44, s18
	v_ashrrev_i32_e32 v2, 1, v0
	v_and_b32_e32 v2, 0xffffffc0, v2
	v_lshrrev_b32_e32 v3, 3, v0
	v_and_b32_e32 v0, 0x5f, v0
	v_add_u32_e32 v2, s14, v2
	s_addc_u32 s3, s45, s19
	v_lshlrev_b32_e32 v0, 1, v0
	v_and_or_b32 v2, v3, 4, v2
	v_lshl_add_u64 v[4:5], s[2:3], 0, v[0:1]
	v_cvt_f16_f32_e32 v0, v160
	v_ashrrev_i32_e32 v3, 31, v2
	v_lshlrev_b64 v[6:7], 11, v[2:3]
	v_lshl_add_u64 v[6:7], v[4:5], 0, v[6:7]
	global_store_short v[6:7], v0, off
	v_cvt_f16_f32_e32 v0, v161
	v_or_b32_e32 v8, 1, v2
	v_ashrrev_i32_e32 v9, 31, v8
	v_lshlrev_b64 v[8:9], 11, v[8:9]
	v_lshl_add_u64 v[8:9], v[4:5], 0, v[8:9]
	global_store_short v[8:9], v0, off
	v_cvt_f16_f32_e32 v0, v158
	v_or_b32_e32 v10, 2, v2
	v_ashrrev_i32_e32 v11, 31, v10
	v_lshlrev_b64 v[10:11], 11, v[10:11]
	v_lshl_add_u64 v[10:11], v[4:5], 0, v[10:11]
	global_store_short v[10:11], v0, off
	v_cvt_f16_f32_e32 v0, v159
	v_or_b32_e32 v12, 3, v2
	v_ashrrev_i32_e32 v13, 31, v12
	v_lshlrev_b64 v[12:13], 11, v[12:13]
	v_lshl_add_u64 v[12:13], v[4:5], 0, v[12:13]
	global_store_short v[12:13], v0, off
	v_cvt_f16_f32_e32 v0, v156
	v_or_b32_e32 v14, 8, v2
	v_ashrrev_i32_e32 v15, 31, v14
	v_lshlrev_b64 v[14:15], 11, v[14:15]
	v_lshl_add_u64 v[14:15], v[4:5], 0, v[14:15]
	global_store_short v[14:15], v0, off
	v_cvt_f16_f32_e32 v0, v157
	v_or_b32_e32 v16, 9, v2
	v_ashrrev_i32_e32 v17, 31, v16
	v_lshlrev_b64 v[16:17], 11, v[16:17]
	v_lshl_add_u64 v[16:17], v[4:5], 0, v[16:17]
	global_store_short v[16:17], v0, off
	v_cvt_f16_f32_e32 v0, v154
	v_or_b32_e32 v18, 10, v2
	v_ashrrev_i32_e32 v19, 31, v18
	v_lshlrev_b64 v[18:19], 11, v[18:19]
	v_lshl_add_u64 v[18:19], v[4:5], 0, v[18:19]
	global_store_short v[18:19], v0, off
	v_cvt_f16_f32_e32 v0, v155
	v_or_b32_e32 v20, 11, v2
	v_ashrrev_i32_e32 v21, 31, v20
	v_lshlrev_b64 v[20:21], 11, v[20:21]
	v_lshl_add_u64 v[20:21], v[4:5], 0, v[20:21]
	global_store_short v[20:21], v0, off
	v_cvt_f16_f32_e32 v0, v152
	v_or_b32_e32 v22, 16, v2
	v_ashrrev_i32_e32 v23, 31, v22
	v_lshlrev_b64 v[22:23], 11, v[22:23]
	v_lshl_add_u64 v[22:23], v[4:5], 0, v[22:23]
	global_store_short v[22:23], v0, off
	v_cvt_f16_f32_e32 v0, v153
	v_or_b32_e32 v24, 17, v2
	v_ashrrev_i32_e32 v25, 31, v24
	v_lshlrev_b64 v[24:25], 11, v[24:25]
	v_lshl_add_u64 v[24:25], v[4:5], 0, v[24:25]
	global_store_short v[24:25], v0, off
	v_cvt_f16_f32_e32 v0, v150
	v_or_b32_e32 v26, 18, v2
	v_ashrrev_i32_e32 v27, 31, v26
	v_lshlrev_b64 v[26:27], 11, v[26:27]
	v_lshl_add_u64 v[26:27], v[4:5], 0, v[26:27]
	global_store_short v[26:27], v0, off
	v_cvt_f16_f32_e32 v0, v151
	v_or_b32_e32 v28, 19, v2
	v_ashrrev_i32_e32 v29, 31, v28
	v_lshlrev_b64 v[28:29], 11, v[28:29]
	v_lshl_add_u64 v[28:29], v[4:5], 0, v[28:29]
	global_store_short v[28:29], v0, off
	v_cvt_f16_f32_e32 v0, v148
	v_or_b32_e32 v30, 24, v2
	v_ashrrev_i32_e32 v31, 31, v30
	v_lshlrev_b64 v[30:31], 11, v[30:31]
	v_lshl_add_u64 v[30:31], v[4:5], 0, v[30:31]
	global_store_short v[30:31], v0, off
	v_cvt_f16_f32_e32 v0, v149
	v_or_b32_e32 v32, 25, v2
	v_ashrrev_i32_e32 v33, 31, v32
	v_lshlrev_b64 v[32:33], 11, v[32:33]
	v_lshl_add_u64 v[32:33], v[4:5], 0, v[32:33]
	global_store_short v[32:33], v0, off
	v_cvt_f16_f32_e32 v0, v146
	v_or_b32_e32 v34, 26, v2
	v_ashrrev_i32_e32 v35, 31, v34
	v_lshlrev_b64 v[34:35], 11, v[34:35]
	v_lshl_add_u64 v[34:35], v[4:5], 0, v[34:35]
	global_store_short v[34:35], v0, off
	v_cvt_f16_f32_e32 v0, v147
	v_or_b32_e32 v36, 27, v2
	v_ashrrev_i32_e32 v37, 31, v36
	v_lshlrev_b64 v[36:37], 11, v[36:37]
	v_lshl_add_u64 v[36:37], v[4:5], 0, v[36:37]
	global_store_short v[36:37], v0, off
	v_cvt_f16_f32_e32 v0, v144
	v_cvt_f16_f32_e32 v3, v145
	v_cvt_f16_f32_e32 v38, v142
	v_cvt_f16_f32_e32 v39, v143
	global_store_short v[6:7], v0, off offset:64
	global_store_short v[8:9], v3, off offset:64
	global_store_short v[10:11], v38, off offset:64
	global_store_short v[12:13], v39, off offset:64
	v_cvt_f16_f32_e32 v0, v140
	v_cvt_f16_f32_e32 v3, v141
	v_cvt_f16_f32_e32 v6, v138
	v_cvt_f16_f32_e32 v7, v139
	global_store_short v[14:15], v0, off offset:64
	global_store_short v[16:17], v3, off offset:64
	global_store_short v[18:19], v6, off offset:64
	global_store_short v[20:21], v7, off offset:64
	v_cvt_f16_f32_e32 v0, v136
	v_cvt_f16_f32_e32 v3, v137
	v_cvt_f16_f32_e32 v6, v134
	v_cvt_f16_f32_e32 v7, v135
	global_store_short v[22:23], v0, off offset:64
	global_store_short v[24:25], v3, off offset:64
	global_store_short v[26:27], v6, off offset:64
	global_store_short v[28:29], v7, off offset:64
	v_cvt_f16_f32_e32 v0, v132
	v_cvt_f16_f32_e32 v3, v133
	v_cvt_f16_f32_e32 v6, v130
	v_cvt_f16_f32_e32 v7, v131
	global_store_short v[30:31], v0, off offset:64
;   __device__ __forceinline__ const float* x() const { return (const float*)(const __attribute__((address_space(1))) float*)kp[0]; }
;   __device__ __forceinline__ half_t* mm() const { return (half_t*)(ws() + OFF_mm); }
; __device__ __forceinline__ void phase_merge(const KP& p, char* smem, int* q, int xcc) {
;     ...
;     int tidx = threadIdx.x;
;     asm volatile("" : "+v"(tidx));
;     const int lane = tidx & 63, wid = tidx >> 6, wm = wid >> 1, wn = wid & 1;
; #pragma unroll
;     for (int mi = 0; mi < 2; ++mi)
; #pragma unroll
;       for (int ni = 0; ni < 2; ++ni)
; #pragma unroll
;         for (int r = 0; r < 16; ++r) {
;           const int row = wm * 64 + mi * 32 + (r & 3) + 8 * (r >> 2) + 4 * (lane >> 5);
;           const int col = wn * 64 + ni * 32 + (lane & 31);
;           p.mm()[(size_t)(m0 + row) * DM + n0 + col] = (half_t)tot[mi][ni][r];
;         }
	global_store_short v[32:33], v3, off offset:64
	global_store_short v[34:35], v6, off offset:64
	global_store_short v[36:37], v7, off offset:64
	v_or_b32_e32 v6, 32, v2
	v_cvt_f16_f32_e32 v0, v128
	v_ashrrev_i32_e32 v7, 31, v6
	v_lshlrev_b64 v[6:7], 11, v[6:7]
	v_lshl_add_u64 v[6:7], v[4:5], 0, v[6:7]
	global_store_short v[6:7], v0, off
	v_cvt_f16_f32_e32 v0, v129
	v_or_b32_e32 v8, 33, v2
	v_ashrrev_i32_e32 v9, 31, v8
	v_lshlrev_b64 v[8:9], 11, v[8:9]
	v_lshl_add_u64 v[8:9], v[4:5], 0, v[8:9]
	global_store_short v[8:9], v0, off
	v_cvt_f16_f32_e32 v0, v126
	v_or_b32_e32 v10, 34, v2
	v_ashrrev_i32_e32 v11, 31, v10
	v_lshlrev_b64 v[10:11], 11, v[10:11]
	v_lshl_add_u64 v[10:11], v[4:5], 0, v[10:11]
	global_store_short v[10:11], v0, off
	v_cvt_f16_f32_e32 v0, v127
	v_or_b32_e32 v12, 35, v2
	v_ashrrev_i32_e32 v13, 31, v12
	v_lshlrev_b64 v[12:13], 11, v[12:13]
	v_lshl_add_u64 v[12:13], v[4:5], 0, v[12:13]
	global_store_short v[12:13], v0, off
	v_cvt_f16_f32_e32 v0, v124
	v_or_b32_e32 v14, 40, v2
	v_ashrrev_i32_e32 v15, 31, v14
	v_lshlrev_b64 v[14:15], 11, v[14:15]
	v_lshl_add_u64 v[14:15], v[4:5], 0, v[14:15]
	global_store_short v[14:15], v0, off
	v_cvt_f16_f32_e32 v0, v125
	v_or_b32_e32 v16, 41, v2
	v_ashrrev_i32_e32 v17, 31, v16
	v_lshlrev_b64 v[16:17], 11, v[16:17]
	v_lshl_add_u64 v[16:17], v[4:5], 0, v[16:17]
	global_store_short v[16:17], v0, off
	v_cvt_f16_f32_e32 v0, v122
	v_or_b32_e32 v18, 42, v2
	v_ashrrev_i32_e32 v19, 31, v18
	v_lshlrev_b64 v[18:19], 11, v[18:19]
	v_lshl_add_u64 v[18:19], v[4:5], 0, v[18:19]
	global_store_short v[18:19], v0, off
	v_cvt_f16_f32_e32 v0, v123
	v_or_b32_e32 v20, 43, v2
	v_ashrrev_i32_e32 v21, 31, v20
	v_lshlrev_b64 v[20:21], 11, v[20:21]
	v_lshl_add_u64 v[20:21], v[4:5], 0, v[20:21]
	global_store_short v[20:21], v0, off
	v_cvt_f16_f32_e32 v0, v120
	v_or_b32_e32 v22, 48, v2
	v_ashrrev_i32_e32 v23, 31, v22
	v_lshlrev_b64 v[22:23], 11, v[22:23]
	v_lshl_add_u64 v[22:23], v[4:5], 0, v[22:23]
	global_store_short v[22:23], v0, off
	v_cvt_f16_f32_e32 v0, v121
	v_or_b32_e32 v24, 49, v2
	v_ashrrev_i32_e32 v25, 31, v24
	v_lshlrev_b64 v[24:25], 11, v[24:25]
	v_lshl_add_u64 v[24:25], v[4:5], 0, v[24:25]
	global_store_short v[24:25], v0, off
	v_cvt_f16_f32_e32 v0, v118
	v_or_b32_e32 v26, 50, v2
	v_ashrrev_i32_e32 v27, 31, v26
	v_lshlrev_b64 v[26:27], 11, v[26:27]
	v_lshl_add_u64 v[26:27], v[4:5], 0, v[26:27]
	global_store_short v[26:27], v0, off
	v_cvt_f16_f32_e32 v0, v119
	v_or_b32_e32 v28, 51, v2
	v_ashrrev_i32_e32 v29, 31, v28
	v_lshlrev_b64 v[28:29], 11, v[28:29]
	v_lshl_add_u64 v[28:29], v[4:5], 0, v[28:29]
	global_store_short v[28:29], v0, off
	v_cvt_f16_f32_e32 v0, v116
	v_or_b32_e32 v30, 56, v2
	v_ashrrev_i32_e32 v31, 31, v30
	v_lshlrev_b64 v[30:31], 11, v[30:31]
	v_lshl_add_u64 v[30:31], v[4:5], 0, v[30:31]
	global_store_short v[30:31], v0, off
	v_cvt_f16_f32_e32 v0, v117
	v_or_b32_e32 v32, 57, v2
	v_ashrrev_i32_e32 v33, 31, v32
	v_lshlrev_b64 v[32:33], 11, v[32:33]
	v_lshl_add_u64 v[32:33], v[4:5], 0, v[32:33]
	global_store_short v[32:33], v0, off
	v_cvt_f16_f32_e32 v0, v114
	v_or_b32_e32 v34, 58, v2
	v_ashrrev_i32_e32 v35, 31, v34
	v_lshlrev_b64 v[34:35], 11, v[34:35]
	v_lshl_add_u64 v[34:35], v[4:5], 0, v[34:35]
	global_store_short v[34:35], v0, off
	v_cvt_f16_f32_e32 v0, v115
	v_or_b32_e32 v2, 59, v2
	v_ashrrev_i32_e32 v3, 31, v2
	v_lshlrev_b64 v[2:3], 11, v[2:3]
	v_lshl_add_u64 v[2:3], v[4:5], 0, v[2:3]
	global_store_short v[2:3], v0, off
	v_cvt_f16_f32_e32 v0, v112
	v_cvt_f16_f32_e32 v4, v113
	v_cvt_f16_f32_e32 v5, v110
	v_cvt_f16_f32_e32 v36, v111
	global_store_short v[6:7], v0, off offset:64
	global_store_short v[8:9], v4, off offset:64
	global_store_short v[10:11], v5, off offset:64
	global_store_short v[12:13], v36, off offset:64
	v_cvt_f16_f32_e32 v0, v108
	v_cvt_f16_f32_e32 v4, v109
	v_cvt_f16_f32_e32 v5, v106
	v_cvt_f16_f32_e32 v6, v107
	global_store_short v[14:15], v0, off offset:64
	global_store_short v[16:17], v4, off offset:64
	global_store_short v[18:19], v5, off offset:64
	global_store_short v[20:21], v6, off offset:64
	v_cvt_f16_f32_e32 v0, v104
	v_cvt_f16_f32_e32 v4, v105
	v_cvt_f16_f32_e32 v5, v102
	v_cvt_f16_f32_e32 v6, v103
	global_store_short v[22:23], v0, off offset:64
	global_store_short v[24:25], v4, off offset:64
	global_store_short v[26:27], v5, off offset:64
	global_store_short v[28:29], v6, off offset:64
	v_cvt_f16_f32_e32 v0, v100
	v_cvt_f16_f32_e32 v4, v101
	v_cvt_f16_f32_e32 v5, v98
	v_cvt_f16_f32_e32 v6, v99
	global_store_short v[30:31], v0, off offset:64
	global_store_short v[32:33], v4, off offset:64
	global_store_short v[34:35], v5, off offset:64
	global_store_short v[2:3], v6, off offset:64
	s_branch .LBB0_1731
